# speedup vs baseline: 1.0894x; 1.0204x over previous
; #define TILE_LOOP(NT) for (int li_ = blockIdx.x >> 3, mtile, ntile; tile_map(li_, NT, mtile, ntile); li_ += gridDim.x >> 3)
; static __device__ __forceinline__ void peer_topk_epilogue(const f32x4 (&acc)[4][4], unsigned* sc, int m0, int hp, float* TV, unsigned char* TI) {
;     ...
;       for (int k = 0; k < 16; ++k) {
;         const bool ta = ka >= kb;
;         const unsigned key = ta ? ka : kb;
;         if (ta) { ++ia; ka = ra_[ia]; } else { ++ib; kb = rb_[ib]; }
;         const unsigned uv = key & ~127u;
;         const float val = __uint_as_float((uv & 0x80000000u) ? (uv & 0x7fffffffu) : ~uv);
;         TV[ob + k] = val; TI[ob + k] = (unsigned char)(127 - (int)(key & 127u));
;       }
; static __device__ __forceinline__ void phase_g5(const Params& p, u16* sm) {
;   const u16* X1b = (const u16*)(p.ws + WS_X1B); const u16* Wq = (const u16*)(p.ws + WS_WPQ);
;   const float* rsq1 = (const float*)(p.ws + WS_RSQ1);
;   const u16* Sk = (const u16*)(p.ws + WS_SKB);
;   float* TV = (float*)(p.ws + WS_TV); unsigned char* TI = (unsigned char*)(p.ws + WS_TI);
;   float* RS1 = (float*)(p.ws + WS_RSQQ);
;   EPI_IDX
;   TILE_LOOP(16) {
;     const int m0 = mtile * 128, n0 = ntile * 128, hp = ntile, hh = hp >> 1, pp = hp & 1;
;     f32x4 acc[4][4]; zero_acc(acc);
;     gemm_main(X1b + (size_t)m0 * 1024, 1024, Wq + (size_t)n0 * 1024, 1024, 1024, acc, sm);
;     {
;       char* smb = (char*)sm;
;       const char* Bb = (const char*)(Sk + (size_t)(pp * 8 + hh) * 16384);
;       const int srow = w * 8 + (lane >> 3), schunk = (((lane & 7) ^ (lane >> 3)) << 3);
;       const unsigned boff = (unsigned)(srow * 128 + schunk) * 2u;
; #pragma unroll
;       for (int st = 0; st < 2; ++st)
; #pragma unroll
;         for (int i = 0; i < 4; ++i)
;           __builtin_amdgcn_global_load_lds((const unsigned*)(Bb + ((size_t)(32 * i) * 128 * 2 + (size_t)st * 128) + boff),
;                                            (unsigned*)(smb + st * 32768 + 16384 + i * 4096 + w * 1024), 16, 0, 0);
.LBB0_635:
	s_or_b64 exec, exec, s[0:1]
	s_add_u32 s44, s60, 0x24000000
	s_addc_u32 s45, s61, 0
	s_add_u32 s46, s60, 0x2a000000
	s_addc_u32 s47, s61, 0
	v_mov_b32_e32 v0, v174
	s_andn2_b64 vcc, exec, s[8:9]
	s_barrier
	s_cbranch_vccnz .LBB0_714
	v_bfe_u32 v2, v0, 3, 3
	v_ashrrev_i32_e32 v4, 6, v0
	v_bitop3_b32 v3, v2, v0, 7 bitop3:0x78
	v_lshlrev_b32_e32 v3, 4, v3
	v_lshlrev_b32_e32 v8, 11, v4
	v_lshlrev_b32_e32 v2, 8, v2
	v_or3_b32 v64, v2, v8, v3
	v_mov_b32_e32 v65, 0
	v_lshl_add_u64 v[2:3], s[60:61], 0, v[64:65]
	s_mov_b64 s[0:1], 0x3d360000
	v_and_b32_e32 v1, 63, v0
	v_and_b32_e32 v5, 15, v0
	v_lshl_add_u64 v[66:67], v[2:3], 0, s[0:1]
	v_ashrrev_i32_e32 v2, 1, v0
	s_movk_i32 s0, 0xffc0
	v_bfe_u32 v6, v0, 4, 2
	v_and_or_b32 v74, v2, s0, v5
	v_cmp_gt_u32_e64 s[0:1], 16, v1
	v_bfe_u32 v1, v0, 5, 1
	v_readlane_b32 s4, v224, 0
	v_and_b32_e32 v7, 7, v0
	v_lshrrev_b32_e32 v2, 1, v0
	v_bitop3_b32 v3, v1, v0, 7 bitop3:0x78
	v_bitop3_b32 v0, v6, v0, 7 bitop3:0x78
	s_lshr_b32 s3, s4, 4
	v_and_b32_e32 v72, 1, v4
	v_and_b32_e32 v2, 8, v2
	v_lshlrev_b32_e32 v77, 4, v3
	v_bitop3_b32 v3, v1, v7, 2 bitop3:0x36
	v_or_b32_e32 v81, 16, v74
	v_or_b32_e32 v84, 32, v74
	v_or_b32_e32 v87, 48, v74
	v_lshlrev_b32_e32 v90, 4, v0
	v_lshlrev_b32_e32 v0, 7, v5
	s_bfe_u32 s2, s4, 0x30003
	s_and_b32 s3, s3, 0x3c0
	v_lshl_or_b32 v2, v72, 15, v2
	v_lshlrev_b32_e32 v75, 7, v74
	v_lshlrev_b32_e32 v78, 4, v3
	v_bitop3_b32 v3, v1, v7, 4 bitop3:0x36
	v_bitop3_b32 v1, v1, v7, 6 bitop3:0x36
	v_lshlrev_b32_e32 v82, 7, v81
	v_lshlrev_b32_e32 v85, 7, v84
	v_lshlrev_b32_e32 v88, 7, v87
	v_lshl_or_b32 v91, v72, 13, v0
	v_bitop3_b32 v0, v6, v7, 4 bitop3:0x36
	s_or_b32 s12, s2, s3
	s_and_b32 s3, s4, 7
	v_lshlrev_b32_e32 v73, 10, v4
	v_add_u32_e32 v76, v2, v75
	v_lshlrev_b32_e32 v79, 4, v3
	v_lshlrev_b32_e32 v80, 4, v1
	v_add_u32_e32 v83, v2, v82
	v_add_u32_e32 v86, v2, v85
	v_add_u32_e32 v89, v2, v88
	v_lshlrev_b32_e32 v92, 4, v0
	s_lshr_b32 s2, s4, 6
	s_lshl_b32 s20, s3, 10
	s_mov_b32 s3, 0
	s_mov_b64 s[4:5], 0x10000
	s_mov_b64 s[8:9], 0x20000
	s_mov_b64 s[10:11], 0x30000
	s_mov_b64 s[14:15], 0x3cf60080
	s_mov_b64 s[16:17], 0x18010080
	s_mov_b64 s[18:19], 0x3cf70080
	s_mov_b64 s[22:23], 0x18020080
	s_mov_b64 s[24:25], 0x3cf80080
	s_mov_b64 s[30:31], 0x18030080
	s_mov_b64 s[34:35], 0x3cf90080
	s_mov_b64 s[36:37], 0x18000100
	s_mov_b64 s[48:49], 0x3cf60100
	s_mov_b64 s[50:51], 0x18010100
	s_mov_b64 s[52:53], 0x3cf70100
	s_mov_b64 s[54:55], 0x18020100
	s_mov_b64 s[64:65], 0x3cf80100
	s_mov_b64 s[66:67], 0x18030100
	s_mov_b64 s[68:69], 0x3cf90100
	s_mov_b64 s[70:71], 0x2000
	s_mov_b64 s[72:73], 0x4000
	s_mov_b64 s[74:75], 0x6000
	s_mov_b64 s[76:77], 0x80
	s_mov_b64 s[78:79], 0x2080
	s_mov_b64 s[80:81], 0x4080
	s_mov_b64 s[82:83], 0x6080
	v_mov_b32_e32 v93, 0x358637bd
	s_mov_b32 s21, 0x800000
	s_movk_i32 s33, 0x204
	s_movk_i32 s42, 0x7f
	s_movk_i32 s43, 0x80
	s_branch .LBB0_639
.LBB0_638:
	s_or_b64 exec, exec, s[84:85]
	s_add_i32 s91, s91, s96
	s_lshr_b32 s2, s91, 1
	s_and_b32 s2, s2, 0x3c0
	s_and_b32 s12, s91, 7
	s_or_b32 s12, s2, s12
	s_lshr_b32 s2, s91, 3
	s_cmpk_lt_u32 s91, 0x600
	s_barrier
	s_cbranch_scc0 .LBB0_714

; __device__ __forceinline__ u32x2 pack4(f32x4 v) { u32x2 o = {cvtpk(v[0], v[1]), cvtpk(v[2], v[3])}; return o; }
; #define MFMA16(a, b, c) __builtin_amdgcn_mfma_f32_16x16x32_bf16((a), (b), (c), 0, 0, 0)
; static __device__ __forceinline__ void peer_topk_epilogue(const f32x4 (&acc)[4][4], unsigned* sc, int m0, int hp, float* TV, unsigned char* TI) {
;     ...
;           const int nl = wc * 64 + nt * 16 + quad * 4 + r;
;           unsigned u = __float_as_uint(acc[mt][nt][r]);
;           u = (u & 0x80000000u) ? ~u : (u | 0x80000000u);
;           sc[(wr * 64 + mt * 16 + l15) * 129 + nl] = (u & ~127u) | (unsigned)(127 - nl);
; static __device__ __forceinline__ void phase_g5(const Params& p, u16* sm) {
;     ...
;       for (int mt = 0; mt < 4; ++mt) {
;         const int ml = wr * 64 + mt * 16 + l15;
;         const float rs = rsqrtf(rsq_1(rsq1, m0 + ml) * (1.f / 1024.f) + EPS);
;         if (ntile == 0 && wc == 0 && quad == 0) RS1[m0 + ml] = rs;
; #pragma unroll
;         for (int nt = 0; nt < 4; ++nt) {
;           const int chunk = nt * 2 + (quad >> 1);
;           f32x4 v = acc[mt][nt] * rs;
;           *(u32x2*)(sm + wc * (256 * 64) + ml * 64 + ((chunk ^ (ml & 7)) << 3) + (quad & 1) * 4) = pack4(v);
;         }
;       }
;       asm volatile("s_waitcnt vmcnt(0)" ::: "memory");
;       __syncthreads();
;       zero_acc(acc);
; #pragma unroll
;       for (int st = 0; st < 2; ++st) {
;         const u16* cA = sm + st * (256 * 64); const u16* cB = cA + 128 * 64;
; #pragma unroll
;         for (int ks = 0; ks < 2; ++ks) {
;           bf16x8 af[4], bfr[4];
;           const int pc = (((ks * 4 + quad) ^ (l15 & 7)) << 3);
; #pragma unroll
;           for (int i = 0; i < 4; ++i) {
;             af[i]  = *(const bf16x8*)(cA + (wr * 64 + i * 16 + l15) * 64 + pc);
;             bfr[i] = *(const bf16x8*)(cB + (wc * 64 + i * 16 + l15) * 64 + pc);
;           }
; #pragma unroll
;           for (int mt = 0; mt < 4; ++mt)
; #pragma unroll
;             for (int nt = 0; nt < 4; ++nt) acc[mt][nt] = MFMA16(bfr[nt], af[mt], acc[mt][nt]);
;         }
;       }
.LBB0_653:
	s_or_b64 exec, exec, s[12:13]
	v_pk_mul_f32 v[14:15], v[14:15], v[16:17] op_sel_hi:[1,0]
	v_pk_mul_f32 v[12:13], v[12:13], v[16:17] op_sel_hi:[1,0]
	v_pk_mul_f32 v[10:11], v[10:11], v[16:17] op_sel_hi:[1,0]
	v_pk_mul_f32 v[8:9], v[8:9], v[16:17] op_sel_hi:[1,0]
	v_pk_mul_f32 v[6:7], v[6:7], v[16:17] op_sel_hi:[1,0]
	v_pk_mul_f32 v[4:5], v[4:5], v[16:17] op_sel_hi:[1,0]
	v_pk_mul_f32 v[2:3], v[2:3], v[16:17] op_sel_hi:[1,0]
	v_pk_mul_f32 v[0:1], v[0:1], v[16:17] op_sel_hi:[1,0]
	v_cvt_pk_bf16_f32 v12, v12, v13
	v_cvt_pk_bf16_f32 v13, v14, v15
	v_add_u32_e32 v14, v89, v77
	v_cvt_pk_bf16_f32 v8, v8, v9
	v_cvt_pk_bf16_f32 v9, v10, v11
	v_add_u32_e32 v10, v89, v78
	v_cvt_pk_bf16_f32 v4, v4, v5
	v_cvt_pk_bf16_f32 v5, v6, v7
	v_add_u32_e32 v6, v89, v79
	v_cvt_pk_bf16_f32 v0, v0, v1
	v_cvt_pk_bf16_f32 v1, v2, v3
	v_add_u32_e32 v2, v89, v80
	ds_write_b64 v14, v[12:13]
	ds_write_b64 v10, v[8:9]
	ds_write_b64 v6, v[4:5]
	ds_write_b64 v2, v[0:1]
	v_add_u32_e32 v64, v90, v91
	v_add_u32_e32 v12, v90, v75
	s_waitcnt vmcnt(0)
	s_waitcnt lgkmcnt(0)
	s_barrier
	ds_read_b128 v[0:3], v64 offset:16384
	ds_read_b128 v[4:7], v64 offset:18432
	ds_read_b128 v[8:11], v12
	ds_read_b128 v[12:15], v12 offset:32768
	ds_read_b128 v[20:23], v64 offset:20480
	ds_read_b128 v[28:31], v64 offset:22528
	v_add_u32_e32 v40, v90, v82
	v_add_u32_e32 v60, v90, v85
	v_add_u32_e32 v106, v90, v88
	ds_read_b128 v[36:39], v40
	ds_read_b128 v[40:43], v40 offset:32768
	ds_read_b128 v[56:59], v60
	ds_read_b128 v[60:63], v60 offset:32768
	ds_read_b128 v[102:105], v106
	ds_read_b128 v[106:109], v106 offset:32768
	v_add_u32_e32 v175, v92, v91
	v_add_u32_e32 v118, v92, v75
	s_waitcnt lgkmcnt(9)
	v_mfma_f32_16x16x32_bf16 v[16:19], v[0:3], v[8:11], 0
	ds_read_b128 v[110:113], v175 offset:16384
	v_add_u32_e32 v134, v92, v82
	v_add_u32_e32 v154, v92, v85
	v_mfma_f32_16x16x32_bf16 v[24:27], v[4:7], v[8:11], 0
	v_add_u32_e32 v170, v92, v88
	s_waitcnt lgkmcnt(8)
	v_mfma_f32_16x16x32_bf16 v[32:35], v[20:23], v[8:11], 0
	s_waitcnt lgkmcnt(7)
	v_mfma_f32_16x16x32_bf16 v[8:11], v[28:31], v[8:11], 0
	s_waitcnt lgkmcnt(6)
	v_mfma_f32_16x16x32_bf16 v[44:47], v[0:3], v[36:39], 0
	v_mfma_f32_16x16x32_bf16 v[48:51], v[4:7], v[36:39], 0
	v_mfma_f32_16x16x32_bf16 v[52:55], v[20:23], v[36:39], 0
	v_mfma_f32_16x16x32_bf16 v[36:39], v[28:31], v[36:39], 0
	s_waitcnt lgkmcnt(4)
	v_mfma_f32_16x16x32_bf16 v[68:71], v[0:3], v[56:59], 0
	v_mfma_f32_16x16x32_bf16 v[94:97], v[4:7], v[56:59], 0
	v_mfma_f32_16x16x32_bf16 v[98:101], v[20:23], v[56:59], 0
	v_mfma_f32_16x16x32_bf16 v[56:59], v[28:31], v[56:59], 0
	s_waitcnt lgkmcnt(2)
	v_mfma_f32_16x16x32_bf16 v[0:3], v[0:3], v[102:105], 0
	v_mfma_f32_16x16x32_bf16 v[4:7], v[4:7], v[102:105], 0
	v_mfma_f32_16x16x32_bf16 v[20:23], v[20:23], v[102:105], 0
	v_mfma_f32_16x16x32_bf16 v[28:31], v[28:31], v[102:105], 0
	ds_read_b128 v[102:105], v175 offset:18432
	ds_read_b128 v[114:117], v118
	ds_read_b128 v[118:121], v118 offset:32768
	ds_read_b128 v[122:125], v175 offset:20480
	ds_read_b128 v[126:129], v175 offset:22528
	s_waitcnt lgkmcnt(3)
	v_mfma_f32_16x16x32_bf16 v[16:19], v[110:113], v[114:117], v[16:19]
	v_mfma_f32_16x16x32_bf16 v[24:27], v[102:105], v[114:117], v[24:27]
	s_waitcnt lgkmcnt(1)
	v_mfma_f32_16x16x32_bf16 v[130:133], v[122:125], v[114:117], v[32:35]
	s_waitcnt lgkmcnt(0)
	v_mfma_f32_16x16x32_bf16 v[8:11], v[126:129], v[114:117], v[8:11]
	s_nop 0
	ds_read_b128 v[32:35], v134
	ds_read_b128 v[114:117], v134 offset:32768
	ds_read_b128 v[134:137], v154
	ds_read_b128 v[138:141], v64 offset:49152
	ds_read_b128 v[142:145], v64 offset:51200
	s_waitcnt lgkmcnt(2)
	v_mfma_f32_16x16x32_bf16 v[68:71], v[110:113], v[134:137], v[68:71]
	ds_read_b128 v[146:149], v64 offset:53248
	ds_read_b128 v[150:153], v64 offset:55296
	ds_read_b128 v[154:157], v154 offset:32768
	ds_read_b128 v[158:161], v175 offset:49152
	ds_read_b128 v[162:165], v175 offset:51200
	ds_read_b128 v[166:169], v170
	ds_read_b128 v[170:173], v170 offset:32768
	ds_read_b128 v[176:179], v175 offset:53248
	ds_read_b128 v[180:183], v175 offset:55296
	v_mfma_f32_16x16x32_bf16 v[94:97], v[102:105], v[134:137], v[94:97]
	s_waitcnt lgkmcnt(0)
	s_barrier
	v_mfma_f32_16x16x32_bf16 v[98:101], v[122:125], v[134:137], v[98:101]
	v_mfma_f32_16x16x32_bf16 v[56:59], v[126:129], v[134:137], v[56:59]
	v_mfma_f32_16x16x32_bf16 v[134:137], v[138:141], v[12:15], v[16:19]
	v_mfma_f32_16x16x32_bf16 v[134:137], v[158:161], v[118:121], v[134:137]
	v_mfma_f32_16x16x32_bf16 v[44:47], v[110:113], v[32:35], v[44:47]
	v_mfma_f32_16x16x32_bf16 v[48:51], v[102:105], v[32:35], v[48:51]
	s_nop 5
	v_xor_b32_e32 v18, -1, v135
	v_cmp_gt_i32_e32 vcc, 0, v135
	v_xor_b32_e32 v19, -1, v134
	v_mfma_f32_16x16x32_bf16 v[52:55], v[122:125], v[32:35], v[52:55]
	v_cndmask_b32_e64 v18, -|v135|, v18, vcc
	v_cmp_gt_i32_e32 vcc, 0, v134
	v_mfma_f32_16x16x32_bf16 v[34:37], v[126:129], v[32:35], v[36:39]
	v_mov_b32_e32 v32, v174
	v_cndmask_b32_e64 v19, -|v134|, v19, vcc
	v_ashrrev_i32_e32 v16, 1, v32
	v_and_b32_e32 v33, 64, v32
	v_lshrrev_b32_e32 v38, 2, v32
	v_and_b32_e32 v16, 0xffffffc0, v16
	v_and_or_b32 v33, v38, 12, v33
	v_and_or_b32 v17, v32, 15, v16
	v_and_b32_e32 v38, 0xffffff80, v18
	v_and_b32_e32 v39, 0xffffff80, v19
	v_mul_lo_u32 v17, v17, s33
	v_mfma_f32_16x16x32_bf16 v[18:21], v[122:125], v[166:169], v[20:23]
	v_lshl_add_u32 v17, v33, 2, v17
	v_cmp_gt_i32_e32 vcc, 0, v137
	s_nop 0
	v_or_b32_e32 v22, v33, v38
	v_or_b32_e32 v23, v33, v39
	v_xor_b32_e32 v22, 0x7e, v22
	v_xor_b32_e32 v23, 0x7f, v23
	ds_write2_b32 v17, v23, v22 offset1:1
	v_xor_b32_e32 v38, -1, v137
	v_mfma_f32_16x16x32_bf16 v[22:25], v[142:145], v[12:15], v[24:27]
	s_nop 2
; #define MFMA16(a, b, c) __builtin_amdgcn_mfma_f32_16x16x32_bf16((a), (b), (c), 0, 0, 0)
; static __device__ __forceinline__ void peer_topk_epilogue(const f32x4 (&acc)[4][4], unsigned* sc, int m0, int hp, float* TV, unsigned char* TI) {
;     ...
;     for (int mt = 0; mt < 4; ++mt)
; #pragma unroll
;       for (int nt = 0; nt < 4; ++nt)
; #pragma unroll
;         for (int r = 0; r < 4; ++r) {
;           const int nl = wc * 64 + nt * 16 + quad * 4 + r;
;           unsigned u = __float_as_uint(acc[mt][nt][r]);
;           u = (u & 0x80000000u) ? ~u : (u | 0x80000000u);
;           sc[(wr * 64 + mt * 16 + l15) * 129 + nl] = (u & ~127u) | (unsigned)(127 - nl);
; static __device__ __forceinline__ void phase_g5(const Params& p, u16* sm) {
;     ...
; #pragma unroll
;           for (int mt = 0; mt < 4; ++mt)
; #pragma unroll
;             for (int nt = 0; nt < 4; ++nt) acc[mt][nt] = MFMA16(bfr[nt], af[mt], acc[mt][nt]);
	v_cndmask_b32_e64 v27, -|v137|, v38, vcc
	v_and_b32_e32 v27, 0xffffff80, v27
	v_mfma_f32_16x16x32_bf16 v[4:7], v[102:105], v[166:169], v[4:7]
	v_xor_b32_e32 v26, -1, v136
	v_cmp_gt_i32_e32 vcc, 0, v136
	v_mfma_f32_16x16x32_bf16 v[102:105], v[146:149], v[12:15], v[130:133]
	s_nop 0
	v_cndmask_b32_e64 v26, -|v136|, v26, vcc
	v_and_b32_e32 v26, 0xffffff80, v26
	v_or_b32_e32 v26, v33, v26
	v_mfma_f32_16x16x32_bf16 v[8:11], v[150:153], v[12:15], v[8:11]
	v_or_b32_e32 v12, v33, v27
	v_xor_b32_e32 v27, 0x7c, v12
	v_mfma_f32_16x16x32_bf16 v[12:15], v[162:165], v[118:121], v[22:25]
	s_nop 2
	v_xor_b32_e32 v22, 0x7d, v26
	ds_write2_b32 v17, v22, v27 offset0:2 offset1:3
	s_nop 2
	v_xor_b32_e32 v26, -1, v13
	v_cmp_gt_i32_e32 vcc, 0, v13
	v_xor_b32_e32 v27, -1, v12
	v_mfma_f32_16x16x32_bf16 v[22:25], v[138:141], v[40:43], v[44:47]
	v_cndmask_b32_e64 v13, -|v13|, v26, vcc
	v_cmp_gt_i32_e32 vcc, 0, v12
	v_and_b32_e32 v13, 0xffffff80, v13
	v_or_b32_e32 v13, v33, v13
	v_cndmask_b32_e64 v12, -|v12|, v27, vcc
	v_and_b32_e32 v12, 0xffffff80, v12
	v_or_b32_e32 v12, v33, v12
	v_xor_b32_e32 v13, 0x6e, v13
	v_xor_b32_e32 v12, 0x6f, v12
	ds_write2_b32 v17, v12, v13 offset0:16 offset1:17
	v_xor_b32_e32 v12, -1, v15
	v_cmp_gt_i32_e32 vcc, 0, v15
	v_xor_b32_e32 v13, -1, v14
	v_mfma_f32_16x16x32_bf16 v[44:47], v[142:145], v[40:43], v[48:51]
	v_cndmask_b32_e64 v12, -|v15|, v12, vcc
	v_cmp_gt_i32_e32 vcc, 0, v14
	v_and_b32_e32 v26, 0xffffff80, v12
	v_mfma_f32_16x16x32_bf16 v[48:51], v[146:149], v[40:43], v[52:55]
	v_cndmask_b32_e64 v13, -|v14|, v13, vcc
	v_and_b32_e32 v27, 0xffffff80, v13
	v_or_b32_e32 v26, v33, v26
	v_mfma_f32_16x16x32_bf16 v[34:37], v[150:153], v[40:43], v[34:37]
	v_or_b32_e32 v27, v33, v27
	v_xor_b32_e32 v26, 0x6c, v26
	v_xor_b32_e32 v27, 0x6d, v27
	v_mfma_f32_16x16x32_bf16 v[38:41], v[138:141], v[60:63], v[68:71]
	ds_write2_b32 v17, v27, v26 offset0:18 offset1:19
	v_mfma_f32_16x16x32_bf16 v[68:71], v[176:179], v[118:121], v[102:105]
	v_mfma_f32_16x16x32_bf16 v[28:31], v[126:129], v[166:169], v[28:31]
	v_mfma_f32_16x16x32_bf16 v[8:11], v[180:183], v[118:121], v[8:11]
	s_nop 5
	v_xor_b32_e32 v26, -1, v69
	v_cmp_gt_i32_e32 vcc, 0, v69
	v_xor_b32_e32 v27, -1, v68
	v_xor_b32_e32 v42, -1, v71
	v_cndmask_b32_e64 v26, -|v69|, v26, vcc
	v_cmp_gt_i32_e32 vcc, 0, v68
	v_and_b32_e32 v26, 0xffffff80, v26
	v_or_b32_e32 v26, v33, v26
	v_cndmask_b32_e64 v27, -|v68|, v27, vcc
	v_and_b32_e32 v27, 0xffffff80, v27
	v_or_b32_e32 v27, v33, v27
	v_xor_b32_e32 v26, 0x5e, v26
	v_xor_b32_e32 v27, 0x5f, v27
	v_cmp_gt_i32_e32 vcc, 0, v71
	ds_write2_b32 v17, v27, v26 offset0:32 offset1:33
	v_mfma_f32_16x16x32_bf16 v[26:29], v[150:153], v[106:109], v[28:31]
	s_nop 2
	v_xor_b32_e32 v30, -1, v70
	v_cndmask_b32_e64 v31, -|v71|, v42, vcc
	v_cmp_gt_i32_e32 vcc, 0, v70
	v_and_b32_e32 v31, 0xffffff80, v31
	v_or_b32_e32 v31, v33, v31
	v_cndmask_b32_e64 v30, -|v70|, v30, vcc
	v_and_b32_e32 v30, 0xffffff80, v30
	v_or_b32_e32 v30, v33, v30
	v_xor_b32_e32 v31, 0x5c, v31
	v_xor_b32_e32 v30, 0x5d, v30
	ds_write2_b32 v17, v30, v31 offset0:34 offset1:35
	v_xor_b32_e32 v30, -1, v9
	v_cmp_gt_i32_e32 vcc, 0, v9
	v_mfma_f32_16x16x32_bf16 v[0:3], v[110:113], v[166:169], v[0:3]
	v_xor_b32_e32 v31, -1, v8
	v_cndmask_b32_e64 v9, -|v9|, v30, vcc
	v_cmp_gt_i32_e32 vcc, 0, v8
	v_and_b32_e32 v9, 0xffffff80, v9
	v_or_b32_e32 v9, v33, v9
	v_cndmask_b32_e64 v8, -|v8|, v31, vcc
	v_and_b32_e32 v8, 0xffffff80, v8
	v_or_b32_e32 v8, v33, v8
	v_mfma_f32_16x16x32_bf16 v[12:15], v[146:149], v[60:63], v[98:101]
	v_xor_b32_e32 v9, 0x4e, v9
	v_xor_b32_e32 v8, 0x4f, v8
	ds_write2_b32 v17, v8, v9 offset0:48 offset1:49
	v_mfma_f32_16x16x32_bf16 v[0:3], v[138:141], v[106:109], v[0:3]
	v_xor_b32_e32 v8, -1, v11
	v_cmp_gt_i32_e32 vcc, 0, v11
	v_xor_b32_e32 v9, -1, v10
	v_mfma_f32_16x16x32_bf16 v[4:7], v[142:145], v[106:109], v[4:7]
	v_cndmask_b32_e64 v8, -|v11|, v8, vcc
	v_cmp_gt_i32_e32 vcc, 0, v10
	v_and_b32_e32 v8, 0xffffff80, v8
	v_mfma_f32_16x16x32_bf16 v[18:21], v[146:149], v[106:109], v[18:21]
	v_cndmask_b32_e64 v9, -|v10|, v9, vcc
	v_mfma_f32_16x16x32_bf16 v[22:25], v[158:161], v[114:117], v[22:25]
	v_mfma_f32_16x16x32_bf16 v[52:55], v[142:145], v[60:63], v[94:97]
	v_mfma_f32_16x16x32_bf16 v[56:59], v[150:153], v[60:63], v[56:59]
	s_nop 5
	v_cmp_gt_i32_e32 vcc, 0, v23
	v_mfma_f32_16x16x32_bf16 v[60:63], v[176:179], v[154:157], v[12:15]
	v_mfma_f32_16x16x32_bf16 v[12:15], v[158:161], v[170:173], v[0:3]
	s_nop 2
	v_and_b32_e32 v0, 0xffffff80, v9
	v_or_b32_e32 v1, v33, v8
	v_mfma_f32_16x16x32_bf16 v[8:11], v[162:165], v[170:173], v[4:7]
	v_or_b32_e32 v0, v33, v0
	v_xor_b32_e32 v1, 0x4c, v1
	v_xor_b32_e32 v0, 0x4d, v0
	v_mfma_f32_16x16x32_bf16 v[4:7], v[176:179], v[170:173], v[18:21]
	ds_write2_b32 v17, v0, v1 offset0:50 offset1:51
	s_nop 1
	v_xor_b32_e32 v19, -1, v23
	v_xor_b32_e32 v20, -1, v22
	v_cndmask_b32_e64 v19, -|v23|, v19, vcc
	v_cmp_gt_i32_e32 vcc, 0, v22
	v_and_b32_e32 v19, 0xffffff80, v19
	v_or_b32_e32 v19, v33, v19
	v_cndmask_b32_e64 v20, -|v22|, v20, vcc
	v_and_b32_e32 v20, 0xffffff80, v20
	v_or_b32_e32 v20, v33, v20
	v_add_u32_e32 v18, 0x2040, v17
	v_xor_b32_e32 v19, 0x7e, v19
	v_xor_b32_e32 v20, 0x7f, v20
	ds_write2_b32 v18, v20, v19 offset1:1
	v_xor_b32_e32 v19, -1, v25
	v_cmp_gt_i32_e32 vcc, 0, v25
	v_xor_b32_e32 v20, -1, v24
	v_mfma_f32_16x16x32_bf16 v[42:45], v[162:165], v[114:117], v[44:47]
	v_cndmask_b32_e64 v19, -|v25|, v19, vcc
	v_cmp_gt_i32_e32 vcc, 0, v24
	v_and_b32_e32 v19, 0xffffff80, v19
	v_or_b32_e32 v19, v33, v19
	v_cndmask_b32_e64 v20, -|v24|, v20, vcc
	v_and_b32_e32 v20, 0xffffff80, v20
	v_or_b32_e32 v20, v33, v20
	v_add_u32_e32 v18, 0x2048, v17
	v_xor_b32_e32 v19, 0x7c, v19
; static __device__ __forceinline__ void peer_topk_epilogue(const f32x4 (&acc)[4][4], unsigned* sc, int m0, int hp, float* TV, unsigned char* TI) {
;     ...
;     for (int mt = 0; mt < 4; ++mt)
; #pragma unroll
;       for (int nt = 0; nt < 4; ++nt)
; #pragma unroll
;         for (int r = 0; r < 4; ++r) {
;           const int nl = wc * 64 + nt * 16 + quad * 4 + r;
;           unsigned u = __float_as_uint(acc[mt][nt][r]);
;           u = (u & 0x80000000u) ? ~u : (u | 0x80000000u);
;           sc[(wr * 64 + mt * 16 + l15) * 129 + nl] = (u & ~127u) | (unsigned)(127 - nl);
	v_xor_b32_e32 v20, 0x7d, v20
	ds_write2_b32 v18, v20, v19 offset1:1
	v_xor_b32_e32 v19, -1, v43
	v_cmp_gt_i32_e32 vcc, 0, v43
	v_xor_b32_e32 v20, -1, v42
	v_add_u32_e32 v18, 0x2080, v17
	v_cndmask_b32_e64 v19, -|v43|, v19, vcc
	v_cmp_gt_i32_e32 vcc, 0, v42
	v_and_b32_e32 v19, 0xffffff80, v19
	v_or_b32_e32 v19, v33, v19
	v_cndmask_b32_e64 v20, -|v42|, v20, vcc
	v_and_b32_e32 v20, 0xffffff80, v20
	v_or_b32_e32 v20, v33, v20
	v_xor_b32_e32 v19, 0x6e, v19
	v_xor_b32_e32 v20, 0x6f, v20
	ds_write2_b32 v18, v20, v19 offset1:1
	v_xor_b32_e32 v19, -1, v45
	v_cmp_gt_i32_e32 vcc, 0, v45
	v_xor_b32_e32 v20, -1, v44
	v_mfma_f32_16x16x32_bf16 v[46:49], v[176:179], v[114:117], v[48:51]
	v_cndmask_b32_e64 v19, -|v45|, v19, vcc
	v_cmp_gt_i32_e32 vcc, 0, v44
	v_and_b32_e32 v19, 0xffffff80, v19
	v_or_b32_e32 v19, v33, v19
	v_cndmask_b32_e64 v20, -|v44|, v20, vcc
	v_and_b32_e32 v20, 0xffffff80, v20
	v_or_b32_e32 v20, v33, v20
	v_add_u32_e32 v18, 0x2088, v17
	v_xor_b32_e32 v19, 0x6c, v19
	v_xor_b32_e32 v20, 0x6d, v20
	ds_write2_b32 v18, v20, v19 offset1:1
	v_xor_b32_e32 v19, -1, v47
	v_cmp_gt_i32_e32 vcc, 0, v47
	v_xor_b32_e32 v20, -1, v46
	v_add_u32_e32 v18, 0x20c0, v17
	v_cndmask_b32_e64 v19, -|v47|, v19, vcc
	v_cmp_gt_i32_e32 vcc, 0, v46
	v_and_b32_e32 v19, 0xffffff80, v19
	v_or_b32_e32 v19, v33, v19
	v_cndmask_b32_e64 v20, -|v46|, v20, vcc
	v_and_b32_e32 v20, 0xffffff80, v20
	v_or_b32_e32 v20, v33, v20
	v_xor_b32_e32 v19, 0x5e, v19
	v_xor_b32_e32 v20, 0x5f, v20
	ds_write2_b32 v18, v20, v19 offset1:1
	v_xor_b32_e32 v19, -1, v49
	v_cmp_gt_i32_e32 vcc, 0, v49
	v_xor_b32_e32 v20, -1, v48
	v_mfma_f32_16x16x32_bf16 v[34:37], v[180:183], v[114:117], v[34:37]
	v_cndmask_b32_e64 v19, -|v49|, v19, vcc
	v_cmp_gt_i32_e32 vcc, 0, v48
	v_and_b32_e32 v19, 0xffffff80, v19
	v_or_b32_e32 v19, v33, v19
	v_cndmask_b32_e64 v20, -|v48|, v20, vcc
	v_and_b32_e32 v20, 0xffffff80, v20
	v_or_b32_e32 v20, v33, v20
	v_add_u32_e32 v18, 0x20c8, v17
	v_xor_b32_e32 v19, 0x5c, v19
	v_xor_b32_e32 v20, 0x5d, v20
	ds_write2_b32 v18, v20, v19 offset1:1
	v_xor_b32_e32 v19, -1, v35
	v_cmp_gt_i32_e32 vcc, 0, v35
	v_xor_b32_e32 v20, -1, v34
	v_add_u32_e32 v18, 0x2100, v17
	v_cndmask_b32_e64 v19, -|v35|, v19, vcc
	v_cmp_gt_i32_e32 vcc, 0, v34
	v_and_b32_e32 v19, 0xffffff80, v19
	v_or_b32_e32 v19, v33, v19
	v_cndmask_b32_e64 v20, -|v34|, v20, vcc
	v_and_b32_e32 v20, 0xffffff80, v20
	v_or_b32_e32 v20, v33, v20
	v_xor_b32_e32 v19, 0x4e, v19
	v_xor_b32_e32 v20, 0x4f, v20
	ds_write2_b32 v18, v20, v19 offset1:1
	v_xor_b32_e32 v19, -1, v37
	v_cmp_gt_i32_e32 vcc, 0, v37
	v_xor_b32_e32 v20, -1, v36
	v_mfma_f32_16x16x32_bf16 v[38:41], v[158:161], v[154:157], v[38:41]
	v_cndmask_b32_e64 v19, -|v37|, v19, vcc
	v_cmp_gt_i32_e32 vcc, 0, v36
	v_and_b32_e32 v19, 0xffffff80, v19
	v_or_b32_e32 v19, v33, v19
	v_cndmask_b32_e64 v20, -|v36|, v20, vcc
	v_and_b32_e32 v20, 0xffffff80, v20
	v_or_b32_e32 v20, v33, v20
	v_add_u32_e32 v18, 0x2108, v17
	v_xor_b32_e32 v19, 0x4c, v19
	v_xor_b32_e32 v20, 0x4d, v20
	ds_write2_b32 v18, v20, v19 offset1:1
	v_xor_b32_e32 v19, -1, v39
	v_cmp_gt_i32_e32 vcc, 0, v39
	v_xor_b32_e32 v20, -1, v38
	v_add_u32_e32 v18, 0x4080, v17
	v_cndmask_b32_e64 v19, -|v39|, v19, vcc
	v_cmp_gt_i32_e32 vcc, 0, v38
	v_and_b32_e32 v19, 0xffffff80, v19
	v_or_b32_e32 v19, v33, v19
	v_cndmask_b32_e64 v20, -|v38|, v20, vcc
	v_and_b32_e32 v20, 0xffffff80, v20
	v_or_b32_e32 v20, v33, v20
	v_xor_b32_e32 v19, 0x7e, v19
	v_xor_b32_e32 v20, 0x7f, v20
	ds_write2_b32 v18, v20, v19 offset1:1
	v_xor_b32_e32 v19, -1, v41
	v_cmp_gt_i32_e32 vcc, 0, v41
	v_xor_b32_e32 v20, -1, v40
	v_mfma_f32_16x16x32_bf16 v[50:53], v[162:165], v[154:157], v[52:55]
	v_cndmask_b32_e64 v19, -|v41|, v19, vcc
	v_cmp_gt_i32_e32 vcc, 0, v40
	v_and_b32_e32 v19, 0xffffff80, v19
	v_or_b32_e32 v19, v33, v19
	v_cndmask_b32_e64 v20, -|v40|, v20, vcc
	v_and_b32_e32 v20, 0xffffff80, v20
	v_or_b32_e32 v20, v33, v20
	v_add_u32_e32 v18, 0x4088, v17
	v_xor_b32_e32 v19, 0x7c, v19
	v_xor_b32_e32 v20, 0x7d, v20
	ds_write2_b32 v18, v20, v19 offset1:1
	v_xor_b32_e32 v19, -1, v51
	v_cmp_gt_i32_e32 vcc, 0, v51
	v_xor_b32_e32 v20, -1, v50
	v_add_u32_e32 v18, 0x40c0, v17
	v_cndmask_b32_e64 v19, -|v51|, v19, vcc
	v_cmp_gt_i32_e32 vcc, 0, v50
	v_and_b32_e32 v19, 0xffffff80, v19
	v_or_b32_e32 v19, v33, v19
	v_cndmask_b32_e64 v20, -|v50|, v20, vcc
	v_and_b32_e32 v20, 0xffffff80, v20
	v_or_b32_e32 v20, v33, v20
	v_xor_b32_e32 v19, 0x6e, v19
	v_xor_b32_e32 v20, 0x6f, v20
	ds_write2_b32 v18, v20, v19 offset1:1
	v_xor_b32_e32 v19, -1, v53
	v_cmp_gt_i32_e32 vcc, 0, v53
	v_xor_b32_e32 v20, -1, v52
	v_add_u32_e32 v18, 0x40c8, v17
	v_cndmask_b32_e64 v19, -|v53|, v19, vcc
	v_cmp_gt_i32_e32 vcc, 0, v52
	v_and_b32_e32 v19, 0xffffff80, v19
	v_or_b32_e32 v19, v33, v19
	v_cndmask_b32_e64 v20, -|v52|, v20, vcc
	v_and_b32_e32 v20, 0xffffff80, v20
	v_or_b32_e32 v20, v33, v20
	v_xor_b32_e32 v19, 0x6c, v19
	v_xor_b32_e32 v20, 0x6d, v20
	ds_write2_b32 v18, v20, v19 offset1:1
	v_xor_b32_e32 v19, -1, v61
	v_cmp_gt_i32_e32 vcc, 0, v61
	v_xor_b32_e32 v20, -1, v60
	v_add_u32_e32 v18, 0x4100, v17
	v_cndmask_b32_e64 v19, -|v61|, v19, vcc
	v_cmp_gt_i32_e32 vcc, 0, v60
	v_and_b32_e32 v19, 0xffffff80, v19
	v_or_b32_e32 v19, v33, v19
	v_cndmask_b32_e64 v20, -|v60|, v20, vcc
	v_and_b32_e32 v20, 0xffffff80, v20
	v_or_b32_e32 v20, v33, v20
	v_xor_b32_e32 v19, 0x5e, v19
	v_xor_b32_e32 v20, 0x5f, v20
	ds_write2_b32 v18, v20, v19 offset1:1
	v_xor_b32_e32 v19, -1, v63
	v_cmp_gt_i32_e32 vcc, 0, v63
	v_xor_b32_e32 v20, -1, v62
	v_mfma_f32_16x16x32_bf16 v[54:57], v[180:183], v[154:157], v[56:59]
	v_cndmask_b32_e64 v19, -|v63|, v19, vcc
	v_cmp_gt_i32_e32 vcc, 0, v62
	v_and_b32_e32 v19, 0xffffff80, v19
; static __device__ __forceinline__ void peer_topk_epilogue(const f32x4 (&acc)[4][4], unsigned* sc, int m0, int hp, float* TV, unsigned char* TI) {
;     ...
;     for (int mt = 0; mt < 4; ++mt)
; #pragma unroll
;       for (int nt = 0; nt < 4; ++nt)
; #pragma unroll
;         for (int r = 0; r < 4; ++r) {
;           const int nl = wc * 64 + nt * 16 + quad * 4 + r;
;           unsigned u = __float_as_uint(acc[mt][nt][r]);
;           u = (u & 0x80000000u) ? ~u : (u | 0x80000000u);
;           sc[(wr * 64 + mt * 16 + l15) * 129 + nl] = (u & ~127u) | (unsigned)(127 - nl);
;         }
;     __syncthreads();
;     {
;       const int row = tid & 127, half = tid >> 7;
;       unsigned* rp = sc + row * 129 + half * 64;
	v_or_b32_e32 v19, v33, v19
	v_cndmask_b32_e64 v20, -|v62|, v20, vcc
	v_and_b32_e32 v20, 0xffffff80, v20
	v_or_b32_e32 v20, v33, v20
	v_add_u32_e32 v18, 0x4108, v17
	v_xor_b32_e32 v19, 0x5c, v19
	v_xor_b32_e32 v20, 0x5d, v20
	ds_write2_b32 v18, v20, v19 offset1:1
	v_xor_b32_e32 v19, -1, v55
	v_cmp_gt_i32_e32 vcc, 0, v55
	v_xor_b32_e32 v20, -1, v54
	v_add_u32_e32 v18, 0x4140, v17
	v_cndmask_b32_e64 v19, -|v55|, v19, vcc
	v_cmp_gt_i32_e32 vcc, 0, v54
	v_and_b32_e32 v19, 0xffffff80, v19
	v_or_b32_e32 v19, v33, v19
	v_cndmask_b32_e64 v20, -|v54|, v20, vcc
	v_and_b32_e32 v20, 0xffffff80, v20
	v_or_b32_e32 v20, v33, v20
	v_xor_b32_e32 v19, 0x4e, v19
	v_xor_b32_e32 v20, 0x4f, v20
	ds_write2_b32 v18, v20, v19 offset1:1
	v_xor_b32_e32 v19, -1, v57
	v_cmp_gt_i32_e32 vcc, 0, v57
	v_xor_b32_e32 v20, -1, v56
	v_add_u32_e32 v18, 0x4148, v17
	v_cndmask_b32_e64 v19, -|v57|, v19, vcc
	v_cmp_gt_i32_e32 vcc, 0, v56
	v_and_b32_e32 v19, 0xffffff80, v19
	v_or_b32_e32 v19, v33, v19
	v_cndmask_b32_e64 v20, -|v56|, v20, vcc
	v_and_b32_e32 v20, 0xffffff80, v20
	v_or_b32_e32 v20, v33, v20
	v_xor_b32_e32 v19, 0x4c, v19
	v_xor_b32_e32 v20, 0x4d, v20
	ds_write2_b32 v18, v20, v19 offset1:1
	v_xor_b32_e32 v19, -1, v13
	v_cmp_gt_i32_e32 vcc, 0, v13
	v_xor_b32_e32 v20, -1, v12
	v_add_u32_e32 v18, 0x60c0, v17
	v_cndmask_b32_e64 v13, -|v13|, v19, vcc
	v_cmp_gt_i32_e32 vcc, 0, v12
	v_and_b32_e32 v13, 0xffffff80, v13
	v_or_b32_e32 v13, v33, v13
	v_cndmask_b32_e64 v12, -|v12|, v20, vcc
	v_and_b32_e32 v12, 0xffffff80, v12
	v_or_b32_e32 v12, v33, v12
	v_xor_b32_e32 v13, 0x7e, v13
	v_xor_b32_e32 v12, 0x7f, v12
	ds_write2_b32 v18, v12, v13 offset1:1
	v_xor_b32_e32 v13, -1, v15
	v_cmp_gt_i32_e32 vcc, 0, v15
	v_xor_b32_e32 v18, -1, v14
	v_add_u32_e32 v12, 0x60c8, v17
	v_cndmask_b32_e64 v13, -|v15|, v13, vcc
	v_cmp_gt_i32_e32 vcc, 0, v14
	v_and_b32_e32 v13, 0xffffff80, v13
	v_or_b32_e32 v13, v33, v13
	v_cndmask_b32_e64 v14, -|v14|, v18, vcc
	v_and_b32_e32 v14, 0xffffff80, v14
	v_or_b32_e32 v14, v33, v14
	v_xor_b32_e32 v13, 0x7c, v13
	v_xor_b32_e32 v14, 0x7d, v14
	ds_write2_b32 v12, v14, v13 offset1:1
	v_xor_b32_e32 v13, -1, v9
	v_cmp_gt_i32_e32 vcc, 0, v9
	v_xor_b32_e32 v14, -1, v8
	v_add_u32_e32 v12, 0x6100, v17
	v_cndmask_b32_e64 v9, -|v9|, v13, vcc
	v_cmp_gt_i32_e32 vcc, 0, v8
	v_and_b32_e32 v9, 0xffffff80, v9
	v_or_b32_e32 v9, v33, v9
	v_cndmask_b32_e64 v8, -|v8|, v14, vcc
	v_and_b32_e32 v8, 0xffffff80, v8
	v_or_b32_e32 v8, v33, v8
	v_xor_b32_e32 v9, 0x6e, v9
	v_xor_b32_e32 v8, 0x6f, v8
	ds_write2_b32 v12, v8, v9 offset1:1
	v_xor_b32_e32 v9, -1, v11
	v_cmp_gt_i32_e32 vcc, 0, v11
	v_xor_b32_e32 v12, -1, v10
	v_add_u32_e32 v8, 0x6108, v17
	v_cndmask_b32_e64 v9, -|v11|, v9, vcc
	v_cmp_gt_i32_e32 vcc, 0, v10
	v_and_b32_e32 v9, 0xffffff80, v9
	v_or_b32_e32 v9, v33, v9
	v_cndmask_b32_e64 v10, -|v10|, v12, vcc
	v_and_b32_e32 v10, 0xffffff80, v10
	v_or_b32_e32 v10, v33, v10
	v_xor_b32_e32 v9, 0x6c, v9
	v_xor_b32_e32 v10, 0x6d, v10
	ds_write2_b32 v8, v10, v9 offset1:1
	v_xor_b32_e32 v9, -1, v5
	v_cmp_gt_i32_e32 vcc, 0, v5
	v_xor_b32_e32 v10, -1, v4
	v_add_u32_e32 v8, 0x6140, v17
	v_cndmask_b32_e64 v5, -|v5|, v9, vcc
	v_cmp_gt_i32_e32 vcc, 0, v4
	v_and_b32_e32 v5, 0xffffff80, v5
	v_or_b32_e32 v5, v33, v5
	v_cndmask_b32_e64 v4, -|v4|, v10, vcc
	v_and_b32_e32 v4, 0xffffff80, v4
	v_or_b32_e32 v4, v33, v4
	v_xor_b32_e32 v5, 0x5e, v5
	v_xor_b32_e32 v4, 0x5f, v4
	ds_write2_b32 v8, v4, v5 offset1:1
	v_xor_b32_e32 v5, -1, v7
	v_cmp_gt_i32_e32 vcc, 0, v7
	v_xor_b32_e32 v8, -1, v6
	v_mfma_f32_16x16x32_bf16 v[0:3], v[180:183], v[170:173], v[26:29]
	v_cndmask_b32_e64 v5, -|v7|, v5, vcc
	v_cmp_gt_i32_e32 vcc, 0, v6
	v_and_b32_e32 v5, 0xffffff80, v5
	v_or_b32_e32 v5, v33, v5
	v_cndmask_b32_e64 v6, -|v6|, v8, vcc
	v_and_b32_e32 v6, 0xffffff80, v6
	v_or_b32_e32 v6, v33, v6
	v_add_u32_e32 v4, 0x6148, v17
	v_xor_b32_e32 v5, 0x5c, v5
	v_xor_b32_e32 v6, 0x5d, v6
	ds_write2_b32 v4, v6, v5 offset1:1
	v_xor_b32_e32 v5, -1, v1
	v_cmp_gt_i32_e32 vcc, 0, v1
	v_xor_b32_e32 v6, -1, v0
	v_add_u32_e32 v4, 0x6180, v17
	v_cndmask_b32_e64 v1, -|v1|, v5, vcc
	v_cmp_gt_i32_e32 vcc, 0, v0
	v_and_b32_e32 v1, 0xffffff80, v1
	v_or_b32_e32 v1, v33, v1
	v_cndmask_b32_e64 v0, -|v0|, v6, vcc
	v_and_b32_e32 v0, 0xffffff80, v0
	v_or_b32_e32 v0, v33, v0
	v_xor_b32_e32 v1, 0x4e, v1
	v_xor_b32_e32 v0, 0x4f, v0
	ds_write2_b32 v4, v0, v1 offset1:1
	v_xor_b32_e32 v1, -1, v3
	v_cmp_gt_i32_e32 vcc, 0, v3
	v_xor_b32_e32 v4, -1, v2
	v_add_u32_e32 v0, 0x6188, v17
	v_cndmask_b32_e64 v1, -|v3|, v1, vcc
	v_cmp_gt_i32_e32 vcc, 0, v2
	v_and_b32_e32 v1, 0xffffff80, v1
	v_or_b32_e32 v1, v33, v1
	v_cndmask_b32_e64 v2, -|v2|, v4, vcc
	v_and_b32_e32 v2, 0xffffff80, v2
	v_or_b32_e32 v2, v33, v2
	v_xor_b32_e32 v1, 0x4c, v1
	v_xor_b32_e32 v2, 0x4d, v2
	ds_write2_b32 v0, v2, v1 offset1:1
	v_and_b32_e32 v0, 0x7f, v32
	v_lshlrev_b32_e32 v1, 2, v16
	v_mad_u32_u24 v33, v0, s33, v1
	s_waitcnt lgkmcnt(0)
	s_barrier
; __device__ __forceinline__ void sort16_desc(unsigned (&k)[16]) {
; #pragma unroll
;   for (int size = 2; size <= 16; size <<= 1)
; #pragma unroll
;     for (int stride = size >> 1; stride > 0; stride >>= 1)
; #pragma unroll
;       for (int i = 0; i < 16; ++i) {
;         const int j = i ^ stride;
;         if (j > i) {
;           const bool up = (i & size) == 0;
;           const unsigned a = k[i], b = k[j], mx = max(a, b), mn = min(a, b);
;           k[i] = up ? mx : mn; k[j] = up ? mn : mx;
;         }
;       }
; }
; static __device__ __forceinline__ void peer_topk_epilogue(const f32x4 (&acc)[4][4], unsigned* sc, int m0, int hp, float* TV, unsigned char* TI) {
;     ...
;       unsigned k0[16], k1[16], k2[16], k3[16];
; #pragma unroll
;       for (int j = 0; j < 16; ++j) { k0[j] = rp[j]; k1[j] = rp[16 + j]; k2[j] = rp[32 + j]; k3[j] = rp[48 + j]; }
;       sort16_desc(k0); sort16_desc(k1); sort16_desc(k2); sort16_desc(k3);
	ds_read2_b32 v[34:35], v33 offset1:1
	ds_read2_b32 v[36:37], v33 offset0:2 offset1:3
	ds_read2_b32 v[38:39], v33 offset0:4 offset1:5
	ds_read2_b32 v[40:41], v33 offset0:6 offset1:7
	ds_read2_b32 v[42:43], v33 offset0:16 offset1:17
	ds_read2_b32 v[44:45], v33 offset0:18 offset1:19
	ds_read2_b32 v[46:47], v33 offset0:20 offset1:21
	ds_read2_b32 v[48:49], v33 offset0:22 offset1:23
	ds_read2_b32 v[22:23], v33 offset0:32 offset1:33
	ds_read2_b32 v[20:21], v33 offset0:34 offset1:35
	ds_read2_b32 v[18:19], v33 offset0:36 offset1:37
	ds_read2_b32 v[16:17], v33 offset0:38 offset1:39
	ds_read2_b32 v[6:7], v33 offset0:48 offset1:49
	ds_read2_b32 v[4:5], v33 offset0:50 offset1:51
	ds_read2_b32 v[2:3], v33 offset0:52 offset1:53
	ds_read2_b32 v[0:1], v33 offset0:54 offset1:55
	ds_read2_b32 v[50:51], v33 offset0:8 offset1:9
	ds_read2_b32 v[52:53], v33 offset0:10 offset1:11
	ds_read2_b32 v[54:55], v33 offset0:12 offset1:13
	ds_read2_b32 v[56:57], v33 offset0:14 offset1:15
	ds_read2_b32 v[58:59], v33 offset0:24 offset1:25
	ds_read2_b32 v[60:61], v33 offset0:26 offset1:27
	ds_read2_b32 v[62:63], v33 offset0:28 offset1:29
	ds_read2_b32 v[68:69], v33 offset0:30 offset1:31
	ds_read2_b32 v[30:31], v33 offset0:40 offset1:41
	ds_read2_b32 v[28:29], v33 offset0:42 offset1:43
	ds_read2_b32 v[26:27], v33 offset0:44 offset1:45
	ds_read2_b32 v[24:25], v33 offset0:46 offset1:47
	ds_read2_b32 v[14:15], v33 offset0:56 offset1:57
	ds_read2_b32 v[12:13], v33 offset0:58 offset1:59
	ds_read2_b32 v[10:11], v33 offset0:60 offset1:61
	ds_read2_b32 v[8:9], v33 offset0:62 offset1:63
	s_waitcnt lgkmcnt(14)
	v_max_u32_e32 v64, v34, v35
	v_min_u32_e32 v34, v34, v35
	v_max_u32_e32 v35, v36, v37
	v_min_u32_e32 v36, v36, v37
	v_max_u32_e32 v37, v38, v39
	v_min_u32_e32 v38, v38, v39
	v_max_u32_e32 v39, v40, v41
	v_min_u32_e32 v40, v40, v41
	v_max_u32_e32 v41, v50, v51
	v_min_u32_e32 v50, v50, v51
	v_max_u32_e32 v51, v52, v53
	v_min_u32_e32 v52, v52, v53
	s_waitcnt lgkmcnt(13)
	v_max_u32_e32 v53, v54, v55
	v_min_u32_e32 v54, v54, v55
	s_waitcnt lgkmcnt(12)
	v_max_u32_e32 v55, v56, v57
	v_min_u32_e32 v56, v56, v57
	v_max_u32_e32 v99, v42, v43
	v_min_u32_e32 v42, v42, v43
	v_max_u32_e32 v43, v44, v45
	v_min_u32_e32 v44, v44, v45
	v_max_u32_e32 v45, v46, v47
	v_min_u32_e32 v46, v46, v47
	v_max_u32_e32 v47, v48, v49
	v_min_u32_e32 v48, v48, v49
	s_waitcnt lgkmcnt(11)
	v_max_u32_e32 v49, v58, v59
	v_min_u32_e32 v58, v58, v59
	s_waitcnt lgkmcnt(10)
	v_max_u32_e32 v59, v60, v61
	v_min_u32_e32 v60, v60, v61
	s_waitcnt lgkmcnt(9)
	v_max_u32_e32 v61, v62, v63
	v_min_u32_e32 v62, v62, v63
	s_waitcnt lgkmcnt(8)
	v_max_u32_e32 v63, v68, v69
	v_min_u32_e32 v68, v68, v69
	v_max_u32_e32 v107, v22, v23
	v_min_u32_e32 v22, v22, v23
	v_max_u32_e32 v23, v20, v21
	v_min_u32_e32 v20, v20, v21
	v_max_u32_e32 v21, v18, v19
	v_min_u32_e32 v18, v18, v19
	v_max_u32_e32 v19, v16, v17
	v_min_u32_e32 v16, v16, v17
	s_waitcnt lgkmcnt(7)
	v_max_u32_e32 v17, v30, v31
	v_min_u32_e32 v30, v30, v31
	s_waitcnt lgkmcnt(6)
	v_max_u32_e32 v31, v28, v29
	v_min_u32_e32 v28, v28, v29
	s_waitcnt lgkmcnt(5)
	v_max_u32_e32 v29, v26, v27
	v_min_u32_e32 v26, v26, v27
	s_waitcnt lgkmcnt(4)
	v_max_u32_e32 v27, v24, v25
	v_min_u32_e32 v24, v24, v25
	v_max_u32_e32 v115, v6, v7
	v_min_u32_e32 v6, v6, v7
	v_max_u32_e32 v7, v4, v5
	v_min_u32_e32 v4, v4, v5
	v_max_u32_e32 v5, v2, v3
	v_min_u32_e32 v2, v2, v3
	v_max_u32_e32 v3, v0, v1
	v_min_u32_e32 v0, v0, v1
	s_waitcnt lgkmcnt(3)
	v_max_u32_e32 v1, v14, v15
	v_min_u32_e32 v14, v14, v15
	s_waitcnt lgkmcnt(2)
	v_max_u32_e32 v15, v12, v13
	v_min_u32_e32 v12, v12, v13
	s_waitcnt lgkmcnt(1)
	v_max_u32_e32 v13, v10, v11
	v_min_u32_e32 v10, v10, v11
	s_waitcnt lgkmcnt(0)
	v_max_u32_e32 v11, v8, v9
	v_min_u32_e32 v8, v8, v9
	v_max_u32_e32 v57, v64, v36
	v_min_u32_e32 v36, v64, v36
	v_max_u32_e32 v64, v34, v35
	v_min_u32_e32 v34, v34, v35
	v_max_u32_e32 v35, v37, v40
	v_min_u32_e32 v37, v37, v40
	v_max_u32_e32 v40, v38, v39
	v_min_u32_e32 v38, v38, v39
	v_max_u32_e32 v39, v41, v52
	v_min_u32_e32 v41, v41, v52
	v_max_u32_e32 v52, v50, v51
	v_min_u32_e32 v50, v50, v51
	v_max_u32_e32 v51, v53, v56
	v_min_u32_e32 v53, v53, v56
	v_max_u32_e32 v56, v54, v55
	v_min_u32_e32 v54, v54, v55
	v_max_u32_e32 v69, v99, v44
	v_min_u32_e32 v44, v99, v44
	v_max_u32_e32 v99, v42, v43
	v_min_u32_e32 v42, v42, v43
	v_max_u32_e32 v43, v45, v48
	v_min_u32_e32 v45, v45, v48
	v_max_u32_e32 v48, v46, v47
	v_min_u32_e32 v46, v46, v47
	v_max_u32_e32 v47, v49, v60
	v_min_u32_e32 v49, v49, v60
	v_max_u32_e32 v60, v58, v59
	v_min_u32_e32 v58, v58, v59
	v_max_u32_e32 v59, v61, v68
	v_min_u32_e32 v61, v61, v68
	v_max_u32_e32 v68, v62, v63
	v_min_u32_e32 v62, v62, v63
	v_max_u32_e32 v25, v107, v20
	v_min_u32_e32 v20, v107, v20
	v_max_u32_e32 v107, v22, v23
	v_min_u32_e32 v22, v22, v23
	v_max_u32_e32 v23, v21, v16
	v_min_u32_e32 v16, v21, v16
	v_max_u32_e32 v21, v18, v19
	v_min_u32_e32 v18, v18, v19
	v_max_u32_e32 v19, v17, v28
	v_min_u32_e32 v17, v17, v28
	v_max_u32_e32 v28, v30, v31
	v_min_u32_e32 v30, v30, v31
	v_max_u32_e32 v31, v29, v24
	v_min_u32_e32 v24, v29, v24
	v_max_u32_e32 v29, v26, v27
	v_min_u32_e32 v26, v26, v27
	v_max_u32_e32 v9, v115, v4
	v_min_u32_e32 v4, v115, v4
	v_max_u32_e32 v115, v6, v7
	v_min_u32_e32 v6, v6, v7
	v_max_u32_e32 v7, v5, v0
	v_min_u32_e32 v0, v5, v0
	v_max_u32_e32 v5, v2, v3
	v_min_u32_e32 v2, v2, v3
	v_max_u32_e32 v3, v1, v12
	v_min_u32_e32 v1, v1, v12
	v_max_u32_e32 v12, v14, v15
	v_min_u32_e32 v14, v14, v15
	v_max_u32_e32 v15, v13, v8
	v_min_u32_e32 v8, v13, v8
	v_max_u32_e32 v13, v10, v11
	v_min_u32_e32 v10, v10, v11
	v_max_u32_e32 v55, v57, v64
	v_min_u32_e32 v57, v57, v64
; __device__ __forceinline__ void sort16_desc(unsigned (&k)[16]) {
; #pragma unroll
;   for (int size = 2; size <= 16; size <<= 1)
; #pragma unroll
;     for (int stride = size >> 1; stride > 0; stride >>= 1)
; #pragma unroll
;       for (int i = 0; i < 16; ++i) {
;         const int j = i ^ stride;
;         if (j > i) {
;           const bool up = (i & size) == 0;
;           const unsigned a = k[i], b = k[j], mx = max(a, b), mn = min(a, b);
;           k[i] = up ? mx : mn; k[j] = up ? mn : mx;
;         }
;       }
; }
; __device__ __forceinline__ void merge16_desc(unsigned (&a)[16], const unsigned (&b)[16]) {
; #pragma unroll
;   for (int i = 0; i < 16; ++i) a[i] = max(a[i], b[15 - i]);
; #pragma unroll
;   for (int stride = 8; stride > 0; stride >>= 1)
; #pragma unroll
;     for (int i = 0; i < 16; ++i) {
;       const int j = i ^ stride;
;       if (j > i) { const unsigned x = a[i], y = a[j]; a[i] = max(x, y); a[j] = min(x, y); }
;     }
; }
	v_max_u32_e32 v64, v36, v34
	v_min_u32_e32 v34, v36, v34
	v_max_u32_e32 v36, v37, v38
	v_min_u32_e32 v37, v37, v38
	v_max_u32_e32 v38, v35, v40
	v_min_u32_e32 v35, v35, v40
	v_max_u32_e32 v40, v39, v52
	v_min_u32_e32 v39, v39, v52
	v_max_u32_e32 v52, v41, v50
	v_min_u32_e32 v41, v41, v50
	v_max_u32_e32 v50, v53, v54
	v_min_u32_e32 v53, v53, v54
	v_max_u32_e32 v54, v51, v56
	v_min_u32_e32 v51, v51, v56
	v_max_u32_e32 v63, v69, v99
	v_min_u32_e32 v69, v69, v99
	v_max_u32_e32 v99, v44, v42
	v_min_u32_e32 v42, v44, v42
	v_max_u32_e32 v44, v45, v46
	v_min_u32_e32 v45, v45, v46
	v_max_u32_e32 v46, v43, v48
	v_min_u32_e32 v43, v43, v48
	v_max_u32_e32 v48, v47, v60
	v_min_u32_e32 v47, v47, v60
	v_max_u32_e32 v60, v49, v58
	v_min_u32_e32 v49, v49, v58
	v_max_u32_e32 v58, v61, v62
	v_min_u32_e32 v61, v61, v62
	v_max_u32_e32 v62, v59, v68
	v_min_u32_e32 v59, v59, v68
	v_max_u32_e32 v27, v25, v107
	v_min_u32_e32 v25, v25, v107
	v_max_u32_e32 v107, v20, v22
	v_min_u32_e32 v20, v20, v22
	v_max_u32_e32 v22, v16, v18
	v_min_u32_e32 v16, v16, v18
	v_max_u32_e32 v18, v23, v21
	v_min_u32_e32 v21, v23, v21
	v_max_u32_e32 v23, v19, v28
	v_min_u32_e32 v19, v19, v28
	v_max_u32_e32 v28, v17, v30
	v_min_u32_e32 v17, v17, v30
	v_max_u32_e32 v30, v24, v26
	v_min_u32_e32 v24, v24, v26
	v_max_u32_e32 v26, v31, v29
	v_min_u32_e32 v29, v31, v29
	v_max_u32_e32 v11, v9, v115
	v_min_u32_e32 v9, v9, v115
	v_max_u32_e32 v115, v4, v6
	v_min_u32_e32 v4, v4, v6
	v_max_u32_e32 v6, v0, v2
	v_min_u32_e32 v0, v0, v2
	v_max_u32_e32 v2, v7, v5
	v_min_u32_e32 v5, v7, v5
	v_max_u32_e32 v7, v3, v12
	v_min_u32_e32 v3, v3, v12
	v_max_u32_e32 v12, v1, v14
	v_min_u32_e32 v1, v1, v14
	v_max_u32_e32 v14, v8, v10
	v_min_u32_e32 v8, v8, v10
	v_max_u32_e32 v10, v15, v13
	v_min_u32_e32 v13, v15, v13
	v_max_u32_e32 v56, v55, v37
	v_min_u32_e32 v37, v55, v37
	v_max_u32_e32 v55, v57, v36
	v_min_u32_e32 v36, v57, v36
	v_max_u32_e32 v57, v64, v35
	v_min_u32_e32 v35, v64, v35
	v_max_u32_e32 v64, v34, v38
	v_min_u32_e32 v34, v34, v38
	v_max_u32_e32 v38, v40, v53
	v_min_u32_e32 v40, v40, v53
	v_max_u32_e32 v53, v39, v50
	v_min_u32_e32 v39, v39, v50
	v_max_u32_e32 v50, v52, v51
	v_min_u32_e32 v51, v52, v51
	v_max_u32_e32 v52, v41, v54
	v_min_u32_e32 v41, v41, v54
	v_max_u32_e32 v68, v63, v45
	v_min_u32_e32 v45, v63, v45
	v_max_u32_e32 v63, v69, v44
	v_min_u32_e32 v44, v69, v44
	v_max_u32_e32 v69, v99, v43
	v_min_u32_e32 v43, v99, v43
	v_max_u32_e32 v99, v42, v46
	v_min_u32_e32 v42, v42, v46
	v_max_u32_e32 v46, v48, v61
	v_min_u32_e32 v48, v48, v61
	v_max_u32_e32 v61, v47, v58
	v_min_u32_e32 v47, v47, v58
	v_max_u32_e32 v58, v60, v59
	v_min_u32_e32 v59, v60, v59
	v_max_u32_e32 v60, v49, v62
	v_min_u32_e32 v49, v49, v62
	v_max_u32_e32 v31, v27, v16
	v_min_u32_e32 v16, v27, v16
	v_max_u32_e32 v27, v25, v22
	v_min_u32_e32 v22, v25, v22
	v_max_u32_e32 v25, v107, v21
	v_min_u32_e32 v21, v107, v21
	v_max_u32_e32 v107, v20, v18
	v_min_u32_e32 v18, v20, v18
	v_max_u32_e32 v20, v23, v24
	v_min_u32_e32 v23, v23, v24
	v_max_u32_e32 v24, v19, v30
	v_min_u32_e32 v19, v19, v30
	v_max_u32_e32 v30, v28, v29
	v_min_u32_e32 v28, v28, v29
	v_max_u32_e32 v29, v17, v26
	v_min_u32_e32 v17, v17, v26
	v_max_u32_e32 v15, v11, v0
	v_min_u32_e32 v0, v11, v0
	v_max_u32_e32 v11, v9, v6
	v_min_u32_e32 v6, v9, v6
	v_max_u32_e32 v9, v115, v5
	v_min_u32_e32 v5, v115, v5
	v_max_u32_e32 v115, v4, v2
	v_min_u32_e32 v2, v4, v2
	v_max_u32_e32 v4, v7, v8
	v_min_u32_e32 v7, v7, v8
	v_max_u32_e32 v8, v3, v14
	v_min_u32_e32 v3, v3, v14
	v_max_u32_e32 v14, v12, v13
	v_min_u32_e32 v12, v12, v13
	v_max_u32_e32 v13, v1, v10
	v_min_u32_e32 v1, v1, v10
	v_max_u32_e32 v54, v56, v57
	v_min_u32_e32 v56, v56, v57
	v_max_u32_e32 v57, v55, v64
	v_min_u32_e32 v55, v55, v64
	v_max_u32_e32 v64, v37, v35
	v_min_u32_e32 v35, v37, v35
	v_max_u32_e32 v37, v36, v34
	v_min_u32_e32 v34, v36, v34
	v_max_u32_e32 v36, v40, v51
	v_min_u32_e32 v40, v40, v51
	v_max_u32_e32 v51, v39, v41
	v_min_u32_e32 v39, v39, v41
	v_max_u32_e32 v41, v38, v50
	v_min_u32_e32 v38, v38, v50
	v_max_u32_e32 v50, v53, v52
	v_min_u32_e32 v52, v53, v52
	v_max_u32_e32 v62, v68, v69
	v_min_u32_e32 v68, v68, v69
	v_max_u32_e32 v69, v63, v99
	v_min_u32_e32 v63, v63, v99
	v_max_u32_e32 v99, v45, v43
	v_min_u32_e32 v43, v45, v43
	v_max_u32_e32 v45, v44, v42
	v_min_u32_e32 v42, v44, v42
	v_max_u32_e32 v44, v48, v59
	v_min_u32_e32 v48, v48, v59
	v_max_u32_e32 v59, v47, v49
	v_min_u32_e32 v47, v47, v49
	v_max_u32_e32 v49, v46, v58
	v_min_u32_e32 v46, v46, v58
	v_max_u32_e32 v58, v61, v60
	v_min_u32_e32 v60, v61, v60
	v_max_u32_e32 v26, v31, v25
	v_min_u32_e32 v25, v31, v25
	v_max_u32_e32 v31, v27, v107
	v_min_u32_e32 v27, v27, v107
	v_max_u32_e32 v107, v16, v21
	v_min_u32_e32 v16, v16, v21
	v_max_u32_e32 v21, v22, v18
	v_min_u32_e32 v18, v22, v18
	v_max_u32_e32 v22, v23, v28
	v_min_u32_e32 v23, v23, v28
	v_max_u32_e32 v28, v19, v17
	v_min_u32_e32 v17, v19, v17
	v_max_u32_e32 v19, v20, v30
	v_min_u32_e32 v20, v20, v30
	v_max_u32_e32 v30, v24, v29
	v_min_u32_e32 v24, v24, v29
	v_max_u32_e32 v10, v15, v9
	v_min_u32_e32 v9, v15, v9
	v_max_u32_e32 v15, v11, v115
	v_min_u32_e32 v11, v11, v115
	v_max_u32_e32 v115, v0, v5
	v_min_u32_e32 v0, v0, v5
	v_max_u32_e32 v5, v6, v2
	v_min_u32_e32 v2, v6, v2
	v_max_u32_e32 v6, v7, v12
	v_min_u32_e32 v7, v7, v12
	v_max_u32_e32 v12, v3, v1
	v_min_u32_e32 v1, v3, v1
	v_max_u32_e32 v3, v4, v14
	v_min_u32_e32 v4, v4, v14
	v_max_u32_e32 v14, v8, v13
	v_min_u32_e32 v8, v8, v13
	v_max_u32_e32 v53, v54, v57
	v_min_u32_e32 v54, v54, v57
	v_max_u32_e32 v57, v56, v55
	v_min_u32_e32 v55, v56, v55
	v_max_u32_e32 v56, v64, v37
	v_min_u32_e32 v37, v64, v37
	v_max_u32_e32 v64, v35, v34
; __device__ __forceinline__ void sort16_desc(unsigned (&k)[16]) {
; #pragma unroll
;   for (int size = 2; size <= 16; size <<= 1)
; #pragma unroll
;     for (int stride = size >> 1; stride > 0; stride >>= 1)
; #pragma unroll
;       for (int i = 0; i < 16; ++i) {
;         const int j = i ^ stride;
;         if (j > i) {
;           const bool up = (i & size) == 0;
;           const unsigned a = k[i], b = k[j], mx = max(a, b), mn = min(a, b);
;           k[i] = up ? mx : mn; k[j] = up ? mn : mx;
;         }
;       }
; }
; __device__ __forceinline__ void merge16_desc(unsigned (&a)[16], const unsigned (&b)[16]) {
; #pragma unroll
;   for (int i = 0; i < 16; ++i) a[i] = max(a[i], b[15 - i]);
; #pragma unroll
;   for (int stride = 8; stride > 0; stride >>= 1)
; #pragma unroll
;     for (int i = 0; i < 16; ++i) {
;       const int j = i ^ stride;
;       if (j > i) { const unsigned x = a[i], y = a[j]; a[i] = max(x, y); a[j] = min(x, y); }
;     }
; }
	v_min_u32_e32 v34, v35, v34
	v_max_u32_e32 v35, v40, v39
	v_min_u32_e32 v39, v40, v39
	v_max_u32_e32 v40, v36, v51
	v_min_u32_e32 v36, v36, v51
	v_max_u32_e32 v51, v38, v52
	v_min_u32_e32 v38, v38, v52
	v_max_u32_e32 v52, v41, v50
	v_min_u32_e32 v41, v41, v50
	v_max_u32_e32 v61, v62, v69
	v_min_u32_e32 v62, v62, v69
	v_max_u32_e32 v69, v68, v63
	v_min_u32_e32 v63, v68, v63
	v_max_u32_e32 v68, v99, v45
	v_min_u32_e32 v45, v99, v45
	v_max_u32_e32 v99, v43, v42
	v_min_u32_e32 v42, v43, v42
	v_max_u32_e32 v43, v48, v47
	v_min_u32_e32 v47, v48, v47
	v_max_u32_e32 v48, v44, v59
	v_min_u32_e32 v44, v44, v59
	v_max_u32_e32 v59, v46, v60
	v_min_u32_e32 v46, v46, v60
	v_max_u32_e32 v60, v49, v58
	v_min_u32_e32 v49, v49, v58
	v_max_u32_e32 v29, v26, v31
	v_min_u32_e32 v26, v26, v31
	v_max_u32_e32 v31, v25, v27
	v_min_u32_e32 v25, v25, v27
	v_max_u32_e32 v27, v107, v21
	v_min_u32_e32 v21, v107, v21
	v_max_u32_e32 v107, v16, v18
	v_min_u32_e32 v16, v16, v18
	v_max_u32_e32 v18, v23, v17
	v_min_u32_e32 v17, v23, v17
	v_max_u32_e32 v23, v22, v28
	v_min_u32_e32 v22, v22, v28
	v_max_u32_e32 v28, v20, v24
	v_min_u32_e32 v20, v20, v24
	v_max_u32_e32 v24, v19, v30
	v_min_u32_e32 v19, v19, v30
	v_max_u32_e32 v13, v10, v15
	v_min_u32_e32 v10, v10, v15
	v_max_u32_e32 v15, v9, v11
	v_min_u32_e32 v9, v9, v11
	v_max_u32_e32 v11, v115, v5
	v_min_u32_e32 v5, v115, v5
	v_max_u32_e32 v115, v0, v2
	v_min_u32_e32 v0, v0, v2
	v_max_u32_e32 v2, v7, v1
	v_min_u32_e32 v1, v7, v1
	v_max_u32_e32 v7, v6, v12
	v_min_u32_e32 v6, v6, v12
	v_max_u32_e32 v12, v4, v8
	v_min_u32_e32 v4, v4, v8
	v_max_u32_e32 v8, v3, v14
	v_min_u32_e32 v3, v3, v14
	v_max_u32_e32 v50, v53, v39
	v_min_u32_e32 v39, v53, v39
	v_max_u32_e32 v53, v54, v35
	v_min_u32_e32 v35, v54, v35
	v_max_u32_e32 v54, v57, v36
	v_min_u32_e32 v36, v57, v36
	v_max_u32_e32 v57, v55, v40
	v_min_u32_e32 v40, v55, v40
	v_max_u32_e32 v55, v56, v38
	v_min_u32_e32 v38, v56, v38
	v_max_u32_e32 v56, v37, v51
	v_min_u32_e32 v37, v37, v51
	v_max_u32_e32 v51, v64, v41
	v_min_u32_e32 v41, v64, v41
	v_max_u32_e32 v64, v34, v52
	v_min_u32_e32 v34, v34, v52
	v_max_u32_e32 v58, v61, v47
	v_min_u32_e32 v47, v61, v47
	v_max_u32_e32 v61, v62, v43
	v_min_u32_e32 v43, v62, v43
	v_max_u32_e32 v62, v69, v44
	v_min_u32_e32 v44, v69, v44
	v_max_u32_e32 v69, v63, v48
	v_min_u32_e32 v48, v63, v48
	v_max_u32_e32 v63, v68, v46
	v_min_u32_e32 v46, v68, v46
	v_max_u32_e32 v68, v45, v59
	v_min_u32_e32 v45, v45, v59
	v_max_u32_e32 v59, v99, v49
	v_min_u32_e32 v49, v99, v49
	v_max_u32_e32 v99, v42, v60
	v_min_u32_e32 v42, v42, v60
	v_max_u32_e32 v30, v29, v17
	v_min_u32_e32 v17, v29, v17
	v_max_u32_e32 v29, v26, v18
	v_min_u32_e32 v18, v26, v18
	v_max_u32_e32 v26, v31, v22
	v_min_u32_e32 v22, v31, v22
	v_max_u32_e32 v31, v25, v23
	v_min_u32_e32 v23, v25, v23
	v_max_u32_e32 v25, v27, v20
	v_min_u32_e32 v20, v27, v20
	v_max_u32_e32 v27, v21, v28
	v_min_u32_e32 v21, v21, v28
	v_max_u32_e32 v28, v107, v19
	v_min_u32_e32 v19, v107, v19
	v_max_u32_e32 v107, v16, v24
	v_min_u32_e32 v16, v16, v24
	v_max_u32_e32 v14, v13, v1
	v_min_u32_e32 v1, v13, v1
	v_max_u32_e32 v13, v10, v2
	v_min_u32_e32 v2, v10, v2
	v_max_u32_e32 v10, v15, v6
	v_min_u32_e32 v6, v15, v6
	v_max_u32_e32 v15, v9, v7
	v_min_u32_e32 v7, v9, v7
	v_max_u32_e32 v9, v11, v4
	v_min_u32_e32 v4, v11, v4
	v_max_u32_e32 v11, v5, v12
	v_min_u32_e32 v5, v5, v12
	v_max_u32_e32 v12, v115, v3
	v_min_u32_e32 v3, v115, v3
	v_max_u32_e32 v115, v0, v8
	v_min_u32_e32 v0, v0, v8
	v_max_u32_e32 v52, v50, v55
	v_min_u32_e32 v50, v50, v55
	v_max_u32_e32 v55, v53, v56
	v_min_u32_e32 v53, v53, v56
	v_max_u32_e32 v56, v54, v51
	v_min_u32_e32 v51, v54, v51
	v_max_u32_e32 v54, v57, v64
	v_min_u32_e32 v57, v57, v64
	v_max_u32_e32 v64, v39, v38
	v_min_u32_e32 v38, v39, v38
	v_max_u32_e32 v39, v35, v37
	v_min_u32_e32 v35, v35, v37
	v_max_u32_e32 v37, v36, v41
	v_min_u32_e32 v36, v36, v41
	v_max_u32_e32 v41, v40, v34
	v_min_u32_e32 v34, v40, v34
	v_max_u32_e32 v60, v58, v63
	v_min_u32_e32 v58, v58, v63
	v_max_u32_e32 v63, v61, v68
	v_min_u32_e32 v61, v61, v68
	v_max_u32_e32 v68, v62, v59
	v_min_u32_e32 v59, v62, v59
	v_max_u32_e32 v62, v69, v99
	v_min_u32_e32 v69, v69, v99
	v_max_u32_e32 v99, v47, v46
	v_min_u32_e32 v46, v47, v46
	v_max_u32_e32 v47, v43, v45
	v_min_u32_e32 v43, v43, v45
	v_max_u32_e32 v45, v44, v49
	v_min_u32_e32 v44, v44, v49
	v_max_u32_e32 v49, v48, v42
	v_min_u32_e32 v42, v48, v42
	v_max_u32_e32 v24, v30, v25
	v_min_u32_e32 v25, v30, v25
	v_max_u32_e32 v30, v29, v27
	v_min_u32_e32 v27, v29, v27
	v_max_u32_e32 v29, v26, v28
	v_min_u32_e32 v26, v26, v28
	v_max_u32_e32 v28, v31, v107
	v_min_u32_e32 v31, v31, v107
	v_max_u32_e32 v107, v17, v20
	v_min_u32_e32 v17, v17, v20
	v_max_u32_e32 v20, v18, v21
	v_min_u32_e32 v18, v18, v21
	v_max_u32_e32 v21, v22, v19
	v_min_u32_e32 v19, v22, v19
	v_max_u32_e32 v22, v23, v16
	v_min_u32_e32 v16, v23, v16
	v_max_u32_e32 v8, v14, v9
	v_min_u32_e32 v9, v14, v9
	v_max_u32_e32 v14, v13, v11
	v_min_u32_e32 v11, v13, v11
	v_max_u32_e32 v13, v10, v12
	v_min_u32_e32 v10, v10, v12
	v_max_u32_e32 v12, v15, v115
	v_min_u32_e32 v15, v15, v115
	v_max_u32_e32 v115, v1, v4
	v_min_u32_e32 v1, v1, v4
	v_max_u32_e32 v4, v2, v5
	v_min_u32_e32 v2, v2, v5
	v_max_u32_e32 v5, v6, v3
	v_min_u32_e32 v3, v6, v3
	v_max_u32_e32 v6, v7, v0
	v_min_u32_e32 v0, v7, v0
	v_max_u32_e32 v40, v52, v56
	v_min_u32_e32 v52, v52, v56
	v_max_u32_e32 v56, v55, v54
	v_min_u32_e32 v54, v55, v54
	v_max_u32_e32 v55, v50, v51
	v_min_u32_e32 v50, v50, v51
	v_max_u32_e32 v51, v53, v57
	v_min_u32_e32 v53, v53, v57
	v_max_u32_e32 v57, v64, v37
	v_min_u32_e32 v37, v64, v37
	v_max_u32_e32 v64, v39, v41
	v_min_u32_e32 v39, v39, v41
; __device__ __forceinline__ void merge16_desc(unsigned (&a)[16], const unsigned (&b)[16]) {
; #pragma unroll
;   for (int i = 0; i < 16; ++i) a[i] = max(a[i], b[15 - i]);
; #pragma unroll
;   for (int stride = 8; stride > 0; stride >>= 1)
; #pragma unroll
;     for (int i = 0; i < 16; ++i) {
;       const int j = i ^ stride;
;       if (j > i) { const unsigned x = a[i], y = a[j]; a[i] = max(x, y); a[j] = min(x, y); }
;     }
; }
	v_max_u32_e32 v41, v38, v36
	v_min_u32_e32 v36, v38, v36
	v_max_u32_e32 v38, v35, v34
	v_min_u32_e32 v34, v35, v34
	v_max_u32_e32 v48, v60, v68
	v_min_u32_e32 v60, v60, v68
	v_max_u32_e32 v68, v63, v62
	v_min_u32_e32 v62, v63, v62
	v_max_u32_e32 v63, v58, v59
	v_min_u32_e32 v58, v58, v59
	v_max_u32_e32 v59, v61, v69
	v_min_u32_e32 v61, v61, v69
	v_max_u32_e32 v69, v99, v45
	v_min_u32_e32 v45, v99, v45
	v_max_u32_e32 v99, v47, v49
	v_min_u32_e32 v47, v47, v49
	v_max_u32_e32 v49, v46, v44
	v_min_u32_e32 v44, v46, v44
	v_max_u32_e32 v46, v43, v42
	v_min_u32_e32 v42, v43, v42
	v_max_u32_e32 v23, v24, v29
	v_min_u32_e32 v24, v24, v29
	v_max_u32_e32 v29, v30, v28
	v_min_u32_e32 v28, v30, v28
	v_max_u32_e32 v30, v25, v26
	v_min_u32_e32 v25, v25, v26
	v_max_u32_e32 v26, v27, v31
	v_min_u32_e32 v27, v27, v31
	v_max_u32_e32 v31, v107, v21
	v_min_u32_e32 v21, v107, v21
	v_max_u32_e32 v107, v20, v22
	v_min_u32_e32 v20, v20, v22
	v_max_u32_e32 v22, v17, v19
	v_min_u32_e32 v17, v17, v19
	v_max_u32_e32 v19, v18, v16
	v_min_u32_e32 v16, v18, v16
	v_max_u32_e32 v7, v8, v13
	v_min_u32_e32 v8, v8, v13
	v_max_u32_e32 v13, v14, v12
	v_min_u32_e32 v12, v14, v12
	v_max_u32_e32 v14, v9, v10
	v_min_u32_e32 v9, v9, v10
	v_max_u32_e32 v10, v11, v15
	v_min_u32_e32 v11, v11, v15
	v_max_u32_e32 v15, v115, v5
	v_min_u32_e32 v5, v115, v5
	v_max_u32_e32 v115, v4, v6
	v_min_u32_e32 v4, v4, v6
	v_max_u32_e32 v6, v1, v3
	v_min_u32_e32 v1, v1, v3
	v_max_u32_e32 v3, v2, v0
	v_min_u32_e32 v0, v2, v0
	v_min_u32_e32 v35, v40, v56
	v_min_u32_e32 v70, v52, v54
	v_min_u32_e32 v71, v55, v51
	v_min_u32_e32 v94, v50, v53
	v_min_u32_e32 v95, v57, v64
	v_min_u32_e32 v96, v37, v39
	v_min_u32_e32 v97, v41, v38
	v_min_u32_e32 v98, v36, v34
	v_min_u32_e32 v43, v48, v68
	v_min_u32_e32 v100, v60, v62
	v_min_u32_e32 v101, v63, v59
	v_min_u32_e32 v102, v58, v61
	v_min_u32_e32 v103, v69, v99
	v_min_u32_e32 v104, v45, v47
	v_min_u32_e32 v105, v49, v46
	v_min_u32_e32 v106, v44, v42
	v_min_u32_e32 v18, v23, v29
	v_min_u32_e32 v108, v24, v28
	v_min_u32_e32 v109, v30, v26
	v_min_u32_e32 v110, v25, v27
	v_min_u32_e32 v111, v31, v107
	v_min_u32_e32 v112, v21, v20
	v_min_u32_e32 v113, v22, v19
	v_min_u32_e32 v114, v17, v16
	v_min_u32_e32 v2, v7, v13
	v_min_u32_e32 v116, v8, v12
	v_min_u32_e32 v117, v14, v10
	v_min_u32_e32 v118, v9, v11
	v_min_u32_e32 v119, v15, v115
	v_min_u32_e32 v120, v5, v4
	v_min_u32_e32 v121, v6, v3
	v_min_u32_e32 v122, v1, v0
	v_max3_u32 v40, v40, v56, v106
	v_max3_u32 v35, v35, v44, v42
	v_max3_u32 v42, v52, v54, v105
	v_max3_u32 v44, v70, v49, v46
	v_max3_u32 v46, v55, v51, v104
	v_max3_u32 v45, v71, v45, v47
	v_max3_u32 v47, v50, v53, v103
	v_max3_u32 v49, v94, v69, v99
	v_max3_u32 v50, v57, v64, v102
	v_max3_u32 v51, v95, v58, v61
	v_max3_u32 v37, v37, v39, v101
	v_max3_u32 v39, v96, v63, v59
	v_max3_u32 v38, v41, v38, v100
	v_max3_u32 v41, v97, v60, v62
	v_max3_u32 v34, v36, v34, v43
	v_max3_u32 v36, v98, v48, v68
	v_max3_u32 v23, v23, v29, v122
	v_max3_u32 v0, v18, v1, v0
	v_max3_u32 v1, v24, v28, v121
	v_max3_u32 v3, v108, v6, v3
	v_max3_u32 v6, v30, v26, v120
	v_max3_u32 v4, v109, v5, v4
	v_max3_u32 v5, v25, v27, v119
	v_max3_u32 v15, v110, v15, v115
	v_max3_u32 v18, v31, v107, v118
	v_max3_u32 v9, v111, v9, v11
	v_max3_u32 v11, v21, v20, v117
	v_max3_u32 v10, v112, v14, v10
	v_max3_u32 v14, v22, v19, v116
	v_max3_u32 v8, v113, v8, v12
	v_max3_u32 v2, v17, v16, v2
	v_max3_u32 v7, v114, v7, v13
	v_max_u32_e32 v43, v40, v50
	v_min_u32_e32 v40, v40, v50
	v_max_u32_e32 v48, v35, v51
	v_min_u32_e32 v35, v35, v51
	v_max_u32_e32 v50, v42, v37
	v_min_u32_e32 v37, v42, v37
	v_max_u32_e32 v42, v44, v39
	v_min_u32_e32 v39, v44, v39
	v_max_u32_e32 v44, v46, v38
	v_min_u32_e32 v38, v46, v38
	v_max_u32_e32 v46, v45, v41
	v_min_u32_e32 v41, v45, v41
	v_max_u32_e32 v45, v47, v34
	v_min_u32_e32 v34, v47, v34
	v_max_u32_e32 v47, v49, v36
	v_min_u32_e32 v36, v49, v36
	v_max_u32_e32 v12, v23, v18
	v_min_u32_e32 v13, v23, v18
	v_max_u32_e32 v16, v0, v9
	v_min_u32_e32 v0, v0, v9
	v_max_u32_e32 v9, v1, v11
	v_min_u32_e32 v1, v1, v11
	v_max_u32_e32 v11, v3, v10
	v_min_u32_e32 v3, v3, v10
	v_max_u32_e32 v10, v6, v14
	v_min_u32_e32 v6, v6, v14
	v_max_u32_e32 v14, v4, v8
	v_min_u32_e32 v4, v4, v8
	v_max_u32_e32 v8, v5, v2
	v_min_u32_e32 v2, v5, v2
	v_max_u32_e32 v5, v15, v7
	v_min_u32_e32 v7, v15, v7
	v_max_u32_e32 v49, v43, v44
	v_min_u32_e32 v43, v43, v44
	v_max_u32_e32 v44, v48, v46
	v_min_u32_e32 v46, v48, v46
	v_max_u32_e32 v48, v50, v45
	v_min_u32_e32 v45, v50, v45
	v_max_u32_e32 v50, v42, v47
	v_min_u32_e32 v42, v42, v47
	v_max_u32_e32 v47, v40, v38
	v_min_u32_e32 v38, v40, v38
	v_max_u32_e32 v40, v35, v41
	v_min_u32_e32 v35, v35, v41
	v_max_u32_e32 v41, v37, v34
	v_min_u32_e32 v34, v37, v34
	v_max_u32_e32 v37, v39, v36
	v_min_u32_e32 v36, v39, v36
	v_max_u32_e32 v15, v12, v10
	v_min_u32_e32 v10, v12, v10
	v_max_u32_e32 v12, v16, v14
	v_min_u32_e32 v14, v16, v14
	v_max_u32_e32 v16, v9, v8
	v_min_u32_e32 v8, v9, v8
	v_max_u32_e32 v9, v11, v5
	v_min_u32_e32 v5, v11, v5
	v_max_u32_e32 v11, v13, v6
	v_min_u32_e32 v6, v13, v6
	v_max_u32_e32 v13, v0, v4
	v_min_u32_e32 v0, v0, v4
	v_max_u32_e32 v4, v1, v2
	v_min_u32_e32 v1, v1, v2
	v_max_u32_e32 v2, v3, v7
	v_min_u32_e32 v3, v3, v7
	v_max_u32_e32 v39, v49, v48
	v_min_u32_e32 v48, v49, v48
	v_max_u32_e32 v49, v44, v50
	v_min_u32_e32 v44, v44, v50
	v_max_u32_e32 v50, v43, v45
	v_min_u32_e32 v43, v43, v45
	v_max_u32_e32 v45, v46, v42
	v_min_u32_e32 v42, v46, v42
	v_max_u32_e32 v46, v47, v41
	v_min_u32_e32 v41, v47, v41
	v_max_u32_e32 v47, v40, v37
	v_min_u32_e32 v37, v40, v37
	v_max_u32_e32 v40, v38, v34
	v_min_u32_e32 v34, v38, v34
; __device__ __forceinline__ void merge16_desc(unsigned (&a)[16], const unsigned (&b)[16]) {
; #pragma unroll
;   for (int i = 0; i < 16; ++i) a[i] = max(a[i], b[15 - i]);
; #pragma unroll
;   for (int stride = 8; stride > 0; stride >>= 1)
; #pragma unroll
;     for (int i = 0; i < 16; ++i) {
;       const int j = i ^ stride;
;       if (j > i) { const unsigned x = a[i], y = a[j]; a[i] = max(x, y); a[j] = min(x, y); }
;     }
; }
; static __device__ __forceinline__ void peer_topk_epilogue(const f32x4 (&acc)[4][4], unsigned* sc, int m0, int hp, float* TV, unsigned char* TI) {
;     ...
;       for (int j = 0; j < 16; ++j) { k0[j] = rp[j]; k1[j] = rp[16 + j]; k2[j] = rp[32 + j]; k3[j] = rp[48 + j]; }
;       sort16_desc(k0); sort16_desc(k1); sort16_desc(k2); sort16_desc(k3);
;       merge16_desc(k0, k1); merge16_desc(k2, k3); merge16_desc(k0, k2);
; #pragma unroll
;       for (int k = 0; k < 16; ++k) rp[k] = k0[k];
;     }
;     __syncthreads();
;     if (tid < 128) {
;       const unsigned* ra_ = sc + tid * 129; const unsigned* rb_ = ra_ + 64;
;       const size_t ob = ((size_t)(m0 + tid) * 16 + hp) * 16;
;       int ia = 0, ib = 0;
;       unsigned ka = ra_[0], kb = rb_[0];
	v_max_u32_e32 v38, v35, v36
	v_min_u32_e32 v35, v35, v36
	v_max_u32_e32 v7, v15, v16
	v_min_u32_e32 v15, v15, v16
	v_max_u32_e32 v16, v12, v9
	v_min_u32_e32 v9, v12, v9
	v_max_u32_e32 v12, v10, v8
	v_min_u32_e32 v8, v10, v8
	v_max_u32_e32 v10, v14, v5
	v_min_u32_e32 v5, v14, v5
	v_max_u32_e32 v14, v11, v4
	v_min_u32_e32 v4, v11, v4
	v_max_u32_e32 v11, v13, v2
	v_min_u32_e32 v2, v13, v2
	v_max_u32_e32 v13, v6, v1
	v_min_u32_e32 v1, v6, v1
	v_max_u32_e32 v6, v0, v3
	v_min_u32_e32 v0, v0, v3
	v_min_u32_e32 v36, v39, v49
	v_min_u32_e32 v51, v48, v44
	v_min_u32_e32 v52, v50, v45
	v_min_u32_e32 v53, v43, v42
	v_min_u32_e32 v54, v46, v47
	v_min_u32_e32 v55, v41, v37
	v_min_u32_e32 v56, v40, v38
	v_min_u32_e32 v57, v34, v35
	v_min_u32_e32 v3, v7, v16
	v_min_u32_e32 v17, v15, v9
	v_min_u32_e32 v18, v12, v10
	v_min_u32_e32 v19, v8, v5
	v_min_u32_e32 v20, v14, v11
	v_min_u32_e32 v21, v4, v2
	v_min_u32_e32 v22, v13, v6
	v_min_u32_e32 v23, v1, v0
	v_max3_u32 v23, v39, v49, v23
	v_max3_u32 v0, v36, v1, v0
	v_max3_u32 v1, v48, v44, v22
	v_max3_u32 v6, v51, v13, v6
	v_max3_u32 v13, v50, v45, v21
	v_max3_u32 v2, v52, v4, v2
	v_max3_u32 v4, v43, v42, v20
	v_max3_u32 v11, v53, v14, v11
	v_max3_u32 v14, v46, v47, v19
	v_max3_u32 v5, v54, v8, v5
	v_max3_u32 v8, v41, v37, v18
	v_max3_u32 v10, v55, v12, v10
	v_max3_u32 v12, v40, v38, v17
	v_max3_u32 v9, v56, v15, v9
	v_max3_u32 v3, v34, v35, v3
	v_max3_u32 v7, v57, v7, v16
	v_max_u32_e32 v15, v23, v14
	v_max_u32_e32 v16, v0, v5
	v_min_u32_e32 v0, v0, v5
	v_max_u32_e32 v5, v1, v8
	v_min_u32_e32 v1, v1, v8
	v_max_u32_e32 v8, v6, v10
	v_min_u32_e32 v6, v6, v10
	v_max_u32_e32 v10, v13, v12
	v_min_u32_e32 v12, v13, v12
	v_max_u32_e32 v13, v2, v9
	v_min_u32_e32 v2, v2, v9
	v_max_u32_e32 v9, v4, v3
	v_min_u32_e32 v3, v4, v3
	v_max_u32_e32 v4, v11, v7
	v_min_u32_e32 v14, v23, v14
	v_min_u32_e32 v7, v11, v7
	v_max_u32_e32 v11, v15, v10
	v_min_u32_e32 v10, v15, v10
	v_max_u32_e32 v15, v16, v13
	v_min_u32_e32 v13, v16, v13
	v_max_u32_e32 v16, v5, v9
	v_min_u32_e32 v5, v5, v9
	v_max_u32_e32 v9, v8, v4
	v_min_u32_e32 v4, v8, v4
	v_max_u32_e32 v8, v14, v12
	v_min_u32_e32 v12, v14, v12
	v_max_u32_e32 v14, v0, v2
	v_min_u32_e32 v0, v0, v2
	v_max_u32_e32 v2, v1, v3
	v_min_u32_e32 v1, v1, v3
	v_max_u32_e32 v3, v6, v7
	v_min_u32_e32 v6, v6, v7
	v_max_u32_e32 v7, v11, v16
	v_min_u32_e32 v11, v11, v16
	v_max_u32_e32 v16, v15, v9
	v_min_u32_e32 v9, v15, v9
	v_max_u32_e32 v15, v10, v5
	v_min_u32_e32 v5, v10, v5
	v_max_u32_e32 v10, v13, v4
	v_min_u32_e32 v4, v13, v4
	v_max_u32_e32 v13, v8, v2
	v_min_u32_e32 v2, v8, v2
	v_max_u32_e32 v8, v14, v3
	v_min_u32_e32 v3, v14, v3
	v_max_u32_e32 v14, v12, v1
	v_min_u32_e32 v1, v12, v1
	v_max_u32_e32 v12, v0, v6
	v_min_u32_e32 v0, v0, v6
	v_max_u32_e32 v6, v7, v16
	v_min_u32_e32 v7, v7, v16
	v_cmp_gt_i32_e32 vcc, s43, v32
	v_max_u32_e32 v16, v11, v9
	v_min_u32_e32 v9, v11, v9
	v_max_u32_e32 v11, v15, v10
	v_min_u32_e32 v10, v15, v10
	v_max_u32_e32 v15, v5, v4
	v_min_u32_e32 v4, v5, v4
	v_max_u32_e32 v5, v13, v8
	v_min_u32_e32 v8, v13, v8
	v_max_u32_e32 v13, v2, v3
	v_min_u32_e32 v2, v2, v3
	v_max_u32_e32 v3, v14, v12
	v_min_u32_e32 v12, v14, v12
	v_max_u32_e32 v14, v1, v0
	v_min_u32_e32 v0, v1, v0
	ds_write2_b32 v33, v6, v7 offset1:1
	ds_write2_b32 v33, v16, v9 offset0:2 offset1:3
	ds_write2_b32 v33, v11, v10 offset0:4 offset1:5
	ds_write2_b32 v33, v15, v4 offset0:6 offset1:7
	ds_write2_b32 v33, v5, v8 offset0:8 offset1:9
	ds_write2_b32 v33, v13, v2 offset0:10 offset1:11
	ds_write2_b32 v33, v3, v12 offset0:12 offset1:13
	ds_write2_b32 v33, v14, v0 offset0:14 offset1:15
	s_waitcnt lgkmcnt(0)
	s_barrier
	s_and_saveexec_b64 s[84:85], vcc
	s_cbranch_execz .LBB0_638
	v_mul_lo_u32 v4, v32, s33
	ds_read2_b32 v[114:115], v4 offset0:0 offset1:1
	ds_read2_b32 v[116:117], v4 offset0:2 offset1:3
	ds_read2_b32 v[118:119], v4 offset0:4 offset1:5
	ds_read2_b32 v[120:121], v4 offset0:6 offset1:7
	ds_read2_b32 v[122:123], v4 offset0:8 offset1:9
	ds_read2_b32 v[124:125], v4 offset0:10 offset1:11
	ds_read2_b32 v[126:127], v4 offset0:12 offset1:13
	ds_read2_b32 v[128:129], v4 offset0:14 offset1:15
	ds_read2_b32 v[130:131], v4 offset0:64 offset1:65
	ds_read2_b32 v[132:133], v4 offset0:66 offset1:67
	ds_read2_b32 v[134:135], v4 offset0:68 offset1:69
	ds_read2_b32 v[136:137], v4 offset0:70 offset1:71
	ds_read2_b32 v[138:139], v4 offset0:72 offset1:73
	ds_read2_b32 v[140:141], v4 offset0:74 offset1:75
	ds_read2_b32 v[142:143], v4 offset0:76 offset1:77
	ds_read2_b32 v[144:145], v4 offset0:78 offset1:79
	v_add_u32_e32 v0, s2, v32
	v_ashrrev_i32_e32 v1, 31, v0
	v_lshlrev_b64 v[0:1], 8, v[0:1]
	v_lshl_or_b32 v0, s90, 4, v0
	v_lshl_add_u64 v[2:3], v[0:1], 2, s[44:45]
	v_lshl_add_u64 v[6:7], s[46:47], 0, v[0:1]
	s_mov_b32 s12, 0x0c0c0400
	s_mov_b32 s13, 0x05040100
	s_waitcnt lgkmcnt(0)
; static __device__ __forceinline__ void peer_topk_epilogue(const f32x4 (&acc)[4][4], unsigned* sc, int m0, int hp, float* TV, unsigned char* TI) {
;     ...
;     if (tid < 128) {
;       const unsigned* ra_ = sc + tid * 129; const unsigned* rb_ = ra_ + 64;
;       const size_t ob = ((size_t)(m0 + tid) * 16 + hp) * 16;
;       int ia = 0, ib = 0;
;       unsigned ka = ra_[0], kb = rb_[0];
;       for (int k = 0; k < 16; ++k) {
;         const bool ta = ka >= kb;
;         const unsigned key = ta ? ka : kb;
;         if (ta) { ++ia; ka = ra_[ia]; } else { ++ib; kb = rb_[ib]; }
;         const unsigned uv = key & ~127u;
;         const float val = __uint_as_float((uv & 0x80000000u) ? (uv & 0x7fffffffu) : ~uv);
;         TV[ob + k] = val; TI[ob + k] = (unsigned char)(127 - (int)(key & 127u));
;       }
	v_max_u32_e32 v146, v114, v145
	v_max_u32_e32 v147, v115, v144
	v_max_u32_e32 v148, v116, v143
	v_max_u32_e32 v149, v117, v142
	v_max_u32_e32 v150, v118, v141
	v_max_u32_e32 v151, v119, v140
	v_max_u32_e32 v152, v120, v139
	v_max_u32_e32 v153, v121, v138
	v_max_u32_e32 v154, v122, v137
	v_max_u32_e32 v155, v123, v136
	v_max_u32_e32 v156, v124, v135
	v_max_u32_e32 v157, v125, v134
	v_max_u32_e32 v158, v126, v133
	v_max_u32_e32 v159, v127, v132
	v_max_u32_e32 v160, v128, v131
	v_max_u32_e32 v161, v129, v130
	v_max_u32_e32 v114, v146, v154
	v_min_u32_e32 v122, v146, v154
	v_max_u32_e32 v115, v147, v155
	v_min_u32_e32 v123, v147, v155
	v_max_u32_e32 v116, v148, v156
	v_min_u32_e32 v124, v148, v156
	v_max_u32_e32 v117, v149, v157
	v_min_u32_e32 v125, v149, v157
	v_max_u32_e32 v118, v150, v158
	v_min_u32_e32 v126, v150, v158
	v_max_u32_e32 v119, v151, v159
	v_min_u32_e32 v127, v151, v159
	v_max_u32_e32 v120, v152, v160
	v_min_u32_e32 v128, v152, v160
	v_max_u32_e32 v121, v153, v161
	v_min_u32_e32 v129, v153, v161
	v_max_u32_e32 v146, v114, v118
	v_min_u32_e32 v150, v114, v118
	v_max_u32_e32 v147, v115, v119
	v_min_u32_e32 v151, v115, v119
	v_max_u32_e32 v148, v116, v120
	v_min_u32_e32 v152, v116, v120
	v_max_u32_e32 v149, v117, v121
	v_min_u32_e32 v153, v117, v121
	v_max_u32_e32 v154, v122, v126
	v_min_u32_e32 v158, v122, v126
	v_max_u32_e32 v155, v123, v127
	v_min_u32_e32 v159, v123, v127
	v_max_u32_e32 v156, v124, v128
	v_min_u32_e32 v160, v124, v128
	v_max_u32_e32 v157, v125, v129
	v_min_u32_e32 v161, v125, v129
	v_max_u32_e32 v114, v146, v148
	v_min_u32_e32 v116, v146, v148
	v_max_u32_e32 v115, v147, v149
	v_min_u32_e32 v117, v147, v149
	v_max_u32_e32 v118, v150, v152
	v_min_u32_e32 v120, v150, v152
	v_max_u32_e32 v119, v151, v153
	v_min_u32_e32 v121, v151, v153
	v_max_u32_e32 v122, v154, v156
	v_min_u32_e32 v124, v154, v156
	v_max_u32_e32 v123, v155, v157
	v_min_u32_e32 v125, v155, v157
	v_max_u32_e32 v126, v158, v160
	v_min_u32_e32 v128, v158, v160
	v_max_u32_e32 v127, v159, v161
	v_min_u32_e32 v129, v159, v161
	v_max_u32_e32 v146, v114, v115
	v_min_u32_e32 v147, v114, v115
	v_max_u32_e32 v148, v116, v117
	v_min_u32_e32 v149, v116, v117
	v_max_u32_e32 v150, v118, v119
	v_min_u32_e32 v151, v118, v119
	v_max_u32_e32 v152, v120, v121
	v_min_u32_e32 v153, v120, v121
	v_max_u32_e32 v154, v122, v123
	v_min_u32_e32 v155, v122, v123
	v_max_u32_e32 v156, v124, v125
	v_min_u32_e32 v157, v124, v125
	v_max_u32_e32 v158, v126, v127
	v_min_u32_e32 v159, v126, v127
	v_max_u32_e32 v160, v128, v129
	v_min_u32_e32 v161, v128, v129
	v_and_b32_e32 v216, 0x7fffff80, v146
	v_bitop3_b32 v217, v146, s42, v146 bitop3:0xcf
	v_cmp_gt_i32_e32 vcc, 0, v146
	v_bitop3_b16 v200, v146, s42, v146 bitop3:0xc
	s_nop 0
	v_cndmask_b32_e32 v184, v217, v216, vcc
	v_and_b32_e32 v216, 0x7fffff80, v147
	v_bitop3_b32 v217, v147, s42, v147 bitop3:0xcf
	v_cmp_gt_i32_e32 vcc, 0, v147
	v_bitop3_b16 v201, v147, s42, v147 bitop3:0xc
	s_nop 0
	v_cndmask_b32_e32 v185, v217, v216, vcc
	v_and_b32_e32 v216, 0x7fffff80, v148
	v_bitop3_b32 v217, v148, s42, v148 bitop3:0xcf
	v_cmp_gt_i32_e32 vcc, 0, v148
	v_bitop3_b16 v202, v148, s42, v148 bitop3:0xc
	s_nop 0
	v_cndmask_b32_e32 v186, v217, v216, vcc
	v_and_b32_e32 v216, 0x7fffff80, v149
	v_bitop3_b32 v217, v149, s42, v149 bitop3:0xcf
	v_cmp_gt_i32_e32 vcc, 0, v149
	v_bitop3_b16 v203, v149, s42, v149 bitop3:0xc
	s_nop 0
	v_cndmask_b32_e32 v187, v217, v216, vcc
	v_and_b32_e32 v216, 0x7fffff80, v150
	v_bitop3_b32 v217, v150, s42, v150 bitop3:0xcf
	v_cmp_gt_i32_e32 vcc, 0, v150
	v_bitop3_b16 v204, v150, s42, v150 bitop3:0xc
	s_nop 0
	v_cndmask_b32_e32 v188, v217, v216, vcc
	v_and_b32_e32 v216, 0x7fffff80, v151
	v_bitop3_b32 v217, v151, s42, v151 bitop3:0xcf
	v_cmp_gt_i32_e32 vcc, 0, v151
	v_bitop3_b16 v205, v151, s42, v151 bitop3:0xc
	s_nop 0
	v_cndmask_b32_e32 v189, v217, v216, vcc
	v_and_b32_e32 v216, 0x7fffff80, v152
	v_bitop3_b32 v217, v152, s42, v152 bitop3:0xcf
	v_cmp_gt_i32_e32 vcc, 0, v152
	v_bitop3_b16 v206, v152, s42, v152 bitop3:0xc
	s_nop 0
	v_cndmask_b32_e32 v190, v217, v216, vcc
	v_and_b32_e32 v216, 0x7fffff80, v153
	v_bitop3_b32 v217, v153, s42, v153 bitop3:0xcf
	v_cmp_gt_i32_e32 vcc, 0, v153
	v_bitop3_b16 v207, v153, s42, v153 bitop3:0xc
	s_nop 0
	v_cndmask_b32_e32 v191, v217, v216, vcc
	v_and_b32_e32 v216, 0x7fffff80, v154
	v_bitop3_b32 v217, v154, s42, v154 bitop3:0xcf
	v_cmp_gt_i32_e32 vcc, 0, v154
	v_bitop3_b16 v208, v154, s42, v154 bitop3:0xc
	s_nop 0
	v_cndmask_b32_e32 v192, v217, v216, vcc
	v_and_b32_e32 v216, 0x7fffff80, v155
	v_bitop3_b32 v217, v155, s42, v155 bitop3:0xcf
	v_cmp_gt_i32_e32 vcc, 0, v155
	v_bitop3_b16 v209, v155, s42, v155 bitop3:0xc
	s_nop 0
	v_cndmask_b32_e32 v193, v217, v216, vcc
	v_and_b32_e32 v216, 0x7fffff80, v156
	v_bitop3_b32 v217, v156, s42, v156 bitop3:0xcf
	v_cmp_gt_i32_e32 vcc, 0, v156
	v_bitop3_b16 v210, v156, s42, v156 bitop3:0xc
	s_nop 0
	v_cndmask_b32_e32 v194, v217, v216, vcc
	v_and_b32_e32 v216, 0x7fffff80, v157
	v_bitop3_b32 v217, v157, s42, v157 bitop3:0xcf
	v_cmp_gt_i32_e32 vcc, 0, v157
	v_bitop3_b16 v211, v157, s42, v157 bitop3:0xc
	s_nop 0
	v_cndmask_b32_e32 v195, v217, v216, vcc
	v_and_b32_e32 v216, 0x7fffff80, v158
	v_bitop3_b32 v217, v158, s42, v158 bitop3:0xcf
	v_cmp_gt_i32_e32 vcc, 0, v158
	v_bitop3_b16 v212, v158, s42, v158 bitop3:0xc
	s_nop 0
	v_cndmask_b32_e32 v196, v217, v216, vcc
	v_and_b32_e32 v216, 0x7fffff80, v159
	v_bitop3_b32 v217, v159, s42, v159 bitop3:0xcf
	v_cmp_gt_i32_e32 vcc, 0, v159
	v_bitop3_b16 v213, v159, s42, v159 bitop3:0xc
	s_nop 0
	v_cndmask_b32_e32 v197, v217, v216, vcc
	v_and_b32_e32 v216, 0x7fffff80, v160
	v_bitop3_b32 v217, v160, s42, v160 bitop3:0xcf
	v_cmp_gt_i32_e32 vcc, 0, v160
	v_bitop3_b16 v214, v160, s42, v160 bitop3:0xc
	s_nop 0
	v_cndmask_b32_e32 v198, v217, v216, vcc
	v_and_b32_e32 v216, 0x7fffff80, v161
	v_bitop3_b32 v217, v161, s42, v161 bitop3:0xcf
	v_cmp_gt_i32_e32 vcc, 0, v161
	v_bitop3_b16 v215, v161, s42, v161 bitop3:0xc
	s_nop 0
	v_cndmask_b32_e32 v199, v217, v216, vcc
	v_perm_b32 v216, v201, v200, s12
	v_perm_b32 v217, v203, v202, s12
	v_perm_b32 v220, v217, v216, s13
	v_perm_b32 v216, v205, v204, s12
	v_perm_b32 v217, v207, v206, s12
	v_perm_b32 v221, v217, v216, s13
	v_perm_b32 v216, v209, v208, s12
	v_perm_b32 v217, v211, v210, s12
	v_perm_b32 v222, v217, v216, s13
	v_perm_b32 v216, v213, v212, s12
	v_perm_b32 v217, v215, v214, s12
	v_perm_b32 v223, v217, v216, s13
	global_store_dwordx4 v[2:3], v[184:187], off
	global_store_dwordx4 v[2:3], v[188:191], off offset:16
	global_store_dwordx4 v[2:3], v[192:195], off offset:32
	global_store_dwordx4 v[2:3], v[196:199], off offset:48
	global_store_dwordx4 v[6:7], v[220:223], off
	s_branch .LBB0_638
